# sample attention: keys that coincide across dilations (same row, same ALiBi bias) are loaded once and carry log2(multiplicity) in the logit, as j=0 already did; stream 95 -> 79 iterations (fold) on to
# speedup vs baseline: 1.0075x; 1.0075x over previous
; __device__ __forceinline__ f32x4 acc1_4(const float* ACC1, int srow, int col) {
;     f32x4 s = *(const f32x4*)(ACC1 + (size_t)srow * N1 + col);
; #pragma unroll
;     for (int kp = 1; kp < 8; ++kp) s += *(const f32x4*)(ACC1 + ((size_t)kp * TS + srow) * N1 + col);
;     return s;
; __device__ __forceinline__ void attn_sample_item(const P& p, int wi, int lane) {
;     ...
;     const int bs = wi >> 5, i = (wi >> 3) & 3, h = wi & 7;
;     const int kg = lane >> 4, li = lane & 15;
;     const int srow = bs * 4 + i;
;     const float* ACC1 = (const float*)(ws + O_ACC1); const float* rstd1 = (const float*)(ws + O_RSTD1);
;     float q[8];
;     { const float rq = rstd1[TP + srow] * (0.08838834764831845f * LOG2E);
;       const f32x4 q0 = acc1_4(ACC1, srow, 3072 + h * 128 + 8 * li), q1 = acc1_4(ACC1, srow, 3072 + h * 128 + 8 * li + 4);
;       q[0] = q0[0] * rq; q[1] = q0[1] * rq; q[2] = q0[2] * rq; q[3] = q0[3] * rq; q[4] = q1[0] * rq; q[5] = q1[1] * rq; q[6] = q1[2] * rq; q[7] = q1[3] * rq; }
;     if (kg == 0) {
;         const float rs = rstd1[TP + srow];
;         float* ko = p.out + OUT_KN + (size_t)srow * 1024 + h * 128 + 8 * li; float* vo = p.out + OUT_VN + (size_t)srow * 1024 + h * 128 + 8 * li;
;         *(f32x4*)ko = acc1_4(ACC1, srow, 4096 + h * 128 + 8 * li) * rs; *(f32x4*)(ko + 4) = acc1_4(ACC1, srow, 4096 + h * 128 + 8 * li + 4) * rs;
;         *(f32x4*)vo = acc1_4(ACC1, srow, 5120 + h * 128 + 8 * li) * rs; *(f32x4*)(vo + 4) = acc1_4(ACC1, srow, 5120 + h * 128 + 8 * li + 4) * rs;
.Las_item:
	s_ashr_i32 s14, s3, 5
	s_bfe_u32 s15, s3, 0x20003
	s_and_b32 s16, s3, 7
	s_lshl_b32 s17, s14, 2
	s_or_b32 s17, s17, s15
	s_lshl_b32 s18, s14, 23
	s_add_u32 s20, s56, s18
	s_addc_u32 s21, s57, 0
	s_add_u32 s24, s58, s18
	s_addc_u32 s25, s59, 0
	s_lshl_b32 s18, s17, 2
	s_add_u32 s18, s18, 0x8000
	s_load_dword s19, s[10:11], s18
	s_lshl_b32 s23, s16, 9
	v_and_b32_e32 v72, 15, v230
	v_lshlrev_b32_e32 v72, 4, v72
	v_bfe_u32 v73, v230, 4, 2
	v_cvt_f32_u32_e32 v202, v73
	v_add_u32_e32 v72, s23, v72
	s_add_u32 s43, s15, 0x800
	s_lshl_b32 s43, s43, 12
	v_add_u32_e32 v203, s43, v72
	s_sub_u32 s43, 0x7a, s16
	s_lshl_b32 s43, s43, 23
	v_mov_b32_e32 v201, s43
	v_mul_f32_e32 v201, 0xbfb8aa3b, v201
	s_mul_i32 s43, s17, 0x6000
	s_add_u32 s43, s43, 0x3000
	v_add_u32_e32 v64, s43, v72
	v_sub_u32_e32 v67, s15, v73
	v_max_i32_e32 v67, 0, v67
	v_lshl_add_u32 v67, s14, 2, v67
	v_lshlrev_b32_e32 v66, 2, v67
	v_add_u32_e32 v66, 0x8000, v66
	v_mul_u32_u24_e32 v65, 0x6000, v67
	v_add_u32_e32 v65, 0x4000, v65
	v_add_u32_e32 v65, v65, v72
	v_lshlrev_b32_e32 v68, 12, v73
	v_sub_u32_e32 v68, v203, v68
	s_mov_b32 s43, 0x7ff000
	v_add_u32_e32 v69, s43, v72
	v_min_u32_e32 v68, v68, v69
	v_add_u32_e32 v69, 0xfff80000, v203
	global_load_dword v70, v66, s[10:11]
	global_load_dwordx4 v[128:131], v68, s[20:21]
	global_load_dwordx4 v[132:135], v68, s[20:21] offset:256
	global_load_dwordx4 v[136:139], v68, s[24:25]
	global_load_dwordx4 v[140:143], v68, s[24:25] offset:256
	global_load_dwordx4 v[144:147], v69, s[20:21]
	global_load_dwordx4 v[148:151], v69, s[20:21] offset:256
	global_load_dwordx4 v[152:155], v69, s[24:25]
	global_load_dwordx4 v[156:159], v69, s[24:25] offset:256
	v_mov_b32_e32 v71, v64
	global_load_dwordx4 v[0:3], v71, s[8:9]
	v_add_u32_e32 v71, 0x300000, v71
	global_load_dwordx4 v[4:7], v71, s[8:9]
	v_add_u32_e32 v71, 0x300000, v71
	global_load_dwordx4 v[8:11], v71, s[8:9]
	v_add_u32_e32 v71, 0x300000, v71
	global_load_dwordx4 v[12:15], v71, s[8:9]
	v_add_u32_e32 v71, 0x300000, v71
	global_load_dwordx4 v[16:19], v71, s[8:9]
	v_add_u32_e32 v71, 0x300000, v71
	global_load_dwordx4 v[20:23], v71, s[8:9]
	v_add_u32_e32 v71, 0x300000, v71
	global_load_dwordx4 v[24:27], v71, s[8:9]
	v_add_u32_e32 v71, 0x300000, v71
	global_load_dwordx4 v[28:31], v71, s[8:9]
	v_mov_b32_e32 v71, v64
	global_load_dwordx4 v[32:35], v71, s[8:9] offset:256
	v_add_u32_e32 v71, 0x300000, v71
	global_load_dwordx4 v[36:39], v71, s[8:9] offset:256
	v_add_u32_e32 v71, 0x300000, v71
	global_load_dwordx4 v[40:43], v71, s[8:9] offset:256
	v_add_u32_e32 v71, 0x300000, v71
	global_load_dwordx4 v[44:47], v71, s[8:9] offset:256
	v_add_u32_e32 v71, 0x300000, v71
	global_load_dwordx4 v[48:51], v71, s[8:9] offset:256
	v_add_u32_e32 v71, 0x300000, v71
	global_load_dwordx4 v[52:55], v71, s[8:9] offset:256
	v_add_u32_e32 v71, 0x300000, v71
	global_load_dwordx4 v[56:59], v71, s[8:9] offset:256
	v_add_u32_e32 v71, 0x300000, v71
	global_load_dwordx4 v[60:63], v71, s[8:9] offset:256
	s_waitcnt vmcnt(8)
	v_add_f32_e32 v160, v0, v4
	v_add_f32_e32 v161, v1, v5
	v_add_f32_e32 v162, v2, v6
	v_add_f32_e32 v163, v3, v7
	v_add_f32_e32 v160, v160, v8
	v_add_f32_e32 v161, v161, v9
	v_add_f32_e32 v162, v162, v10
	v_add_f32_e32 v163, v163, v11
	v_add_f32_e32 v160, v160, v12
	v_add_f32_e32 v161, v161, v13
	v_add_f32_e32 v162, v162, v14
	v_add_f32_e32 v163, v163, v15
	v_add_f32_e32 v160, v160, v16
	v_add_f32_e32 v161, v161, v17
	v_add_f32_e32 v162, v162, v18
	v_add_f32_e32 v163, v163, v19
	v_add_f32_e32 v160, v160, v20
	v_add_f32_e32 v161, v161, v21
	v_add_f32_e32 v162, v162, v22
	v_add_f32_e32 v163, v163, v23
	v_add_f32_e32 v160, v160, v24
	v_add_f32_e32 v161, v161, v25
	v_add_f32_e32 v162, v162, v26
	v_add_f32_e32 v163, v163, v27
	v_add_f32_e32 v160, v160, v28
	v_add_f32_e32 v161, v161, v29
	v_add_f32_e32 v162, v162, v30
	v_add_f32_e32 v163, v163, v31
	v_mov_b32_e32 v71, v65
	global_load_dwordx4 v[0:3], v71, s[8:9]
	v_add_u32_e32 v71, 0x300000, v71
	global_load_dwordx4 v[4:7], v71, s[8:9]
	v_add_u32_e32 v71, 0x300000, v71
	global_load_dwordx4 v[8:11], v71, s[8:9]
	v_add_u32_e32 v71, 0x300000, v71
	global_load_dwordx4 v[12:15], v71, s[8:9]
	v_add_u32_e32 v71, 0x300000, v71
	global_load_dwordx4 v[16:19], v71, s[8:9]
	v_add_u32_e32 v71, 0x300000, v71
	global_load_dwordx4 v[20:23], v71, s[8:9]
	v_add_u32_e32 v71, 0x300000, v71
	global_load_dwordx4 v[24:27], v71, s[8:9]
	v_add_u32_e32 v71, 0x300000, v71
	global_load_dwordx4 v[28:31], v71, s[8:9]
	s_waitcnt vmcnt(8)
	v_add_f32_e32 v164, v32, v36
	v_add_f32_e32 v165, v33, v37
	v_add_f32_e32 v166, v34, v38
	v_add_f32_e32 v167, v35, v39
	v_add_f32_e32 v164, v164, v40
	v_add_f32_e32 v165, v165, v41
	v_add_f32_e32 v166, v166, v42
	v_add_f32_e32 v167, v167, v43
	v_add_f32_e32 v164, v164, v44
	v_add_f32_e32 v165, v165, v45
	v_add_f32_e32 v166, v166, v46
	v_add_f32_e32 v167, v167, v47
	v_add_f32_e32 v164, v164, v48
	v_add_f32_e32 v165, v165, v49
	v_add_f32_e32 v166, v166, v50
	v_add_f32_e32 v167, v167, v51
	v_add_f32_e32 v164, v164, v52
	v_add_f32_e32 v165, v165, v53
	v_add_f32_e32 v166, v166, v54
	v_add_f32_e32 v167, v167, v55
	v_add_f32_e32 v164, v164, v56
	v_add_f32_e32 v165, v165, v57
	v_add_f32_e32 v166, v166, v58
	v_add_f32_e32 v167, v167, v59
	v_add_f32_e32 v164, v164, v60
	v_add_f32_e32 v165, v165, v61
	v_add_f32_e32 v166, v166, v62
	v_add_f32_e32 v167, v167, v63
	v_mov_b32_e32 v71, v65
	global_load_dwordx4 v[32:35], v71, s[8:9] offset:256
	v_add_u32_e32 v71, 0x300000, v71
	global_load_dwordx4 v[36:39], v71, s[8:9] offset:256
	v_add_u32_e32 v71, 0x300000, v71
	global_load_dwordx4 v[40:43], v71, s[8:9] offset:256
	v_add_u32_e32 v71, 0x300000, v71
	global_load_dwordx4 v[44:47], v71, s[8:9] offset:256
	v_add_u32_e32 v71, 0x300000, v71
	global_load_dwordx4 v[48:51], v71, s[8:9] offset:256
	v_add_u32_e32 v71, 0x300000, v71
	global_load_dwordx4 v[52:55], v71, s[8:9] offset:256
	v_add_u32_e32 v71, 0x300000, v71
	global_load_dwordx4 v[56:59], v71, s[8:9] offset:256
	v_add_u32_e32 v71, 0x300000, v71
	global_load_dwordx4 v[60:63], v71, s[8:9] offset:256
	s_waitcnt vmcnt(8)
; __device__ __forceinline__ f32x4 acc1_4(const float* ACC1, int srow, int col) {
;     f32x4 s = *(const f32x4*)(ACC1 + (size_t)srow * N1 + col);
; #pragma unroll
;     for (int kp = 1; kp < 8; ++kp) s += *(const f32x4*)(ACC1 + ((size_t)kp * TS + srow) * N1 + col);
;     return s;
; __device__ __forceinline__ void attn_sample_item(const P& p, int wi, int lane) {
;     ...
;         const float rs = rstd1[TP + srow];
;         float* ko = p.out + OUT_KN + (size_t)srow * 1024 + h * 128 + 8 * li; float* vo = p.out + OUT_VN + (size_t)srow * 1024 + h * 128 + 8 * li;
;         *(f32x4*)ko = acc1_4(ACC1, srow, 4096 + h * 128 + 8 * li) * rs; *(f32x4*)(ko + 4) = acc1_4(ACC1, srow, 4096 + h * 128 + 8 * li + 4) * rs;
;         *(f32x4*)vo = acc1_4(ACC1, srow, 5120 + h * 128 + 8 * li) * rs; *(f32x4*)(vo + 4) = acc1_4(ACC1, srow, 5120 + h * 128 + 8 * li + 4) * rs;
	v_add_f32_e32 v176, v0, v4
	v_add_f32_e32 v177, v1, v5
	v_add_f32_e32 v178, v2, v6
	v_add_f32_e32 v179, v3, v7
	v_add_f32_e32 v176, v176, v8
	v_add_f32_e32 v177, v177, v9
	v_add_f32_e32 v178, v178, v10
	v_add_f32_e32 v179, v179, v11
	v_add_f32_e32 v176, v176, v12
	v_add_f32_e32 v177, v177, v13
	v_add_f32_e32 v178, v178, v14
	v_add_f32_e32 v179, v179, v15
	v_add_f32_e32 v176, v176, v16
	v_add_f32_e32 v177, v177, v17
	v_add_f32_e32 v178, v178, v18
	v_add_f32_e32 v179, v179, v19
	v_add_f32_e32 v176, v176, v20
	v_add_f32_e32 v177, v177, v21
	v_add_f32_e32 v178, v178, v22
	v_add_f32_e32 v179, v179, v23
	v_add_f32_e32 v176, v176, v24
	v_add_f32_e32 v177, v177, v25
	v_add_f32_e32 v178, v178, v26
	v_add_f32_e32 v179, v179, v27
	v_add_f32_e32 v176, v176, v28
	v_add_f32_e32 v177, v177, v29
	v_add_f32_e32 v178, v178, v30
	v_add_f32_e32 v179, v179, v31
	v_add_u32_e32 v71, 0x1000, v65
	global_load_dwordx4 v[0:3], v71, s[8:9]
	v_add_u32_e32 v71, 0x300000, v71
	global_load_dwordx4 v[4:7], v71, s[8:9]
	v_add_u32_e32 v71, 0x300000, v71
	global_load_dwordx4 v[8:11], v71, s[8:9]
	v_add_u32_e32 v71, 0x300000, v71
	global_load_dwordx4 v[12:15], v71, s[8:9]
	v_add_u32_e32 v71, 0x300000, v71
	global_load_dwordx4 v[16:19], v71, s[8:9]
	v_add_u32_e32 v71, 0x300000, v71
	global_load_dwordx4 v[20:23], v71, s[8:9]
	v_add_u32_e32 v71, 0x300000, v71
	global_load_dwordx4 v[24:27], v71, s[8:9]
	v_add_u32_e32 v71, 0x300000, v71
	global_load_dwordx4 v[28:31], v71, s[8:9]
	s_waitcnt vmcnt(8)
	v_add_f32_e32 v180, v32, v36
	v_add_f32_e32 v181, v33, v37
	v_add_f32_e32 v182, v34, v38
	v_add_f32_e32 v183, v35, v39
	v_add_f32_e32 v180, v180, v40
	v_add_f32_e32 v181, v181, v41
	v_add_f32_e32 v182, v182, v42
	v_add_f32_e32 v183, v183, v43
	v_add_f32_e32 v180, v180, v44
	v_add_f32_e32 v181, v181, v45
	v_add_f32_e32 v182, v182, v46
	v_add_f32_e32 v183, v183, v47
	v_add_f32_e32 v180, v180, v48
	v_add_f32_e32 v181, v181, v49
	v_add_f32_e32 v182, v182, v50
	v_add_f32_e32 v183, v183, v51
	v_add_f32_e32 v180, v180, v52
	v_add_f32_e32 v181, v181, v53
	v_add_f32_e32 v182, v182, v54
	v_add_f32_e32 v183, v183, v55
	v_add_f32_e32 v180, v180, v56
	v_add_f32_e32 v181, v181, v57
	v_add_f32_e32 v182, v182, v58
	v_add_f32_e32 v183, v183, v59
	v_add_f32_e32 v180, v180, v60
	v_add_f32_e32 v181, v181, v61
	v_add_f32_e32 v182, v182, v62
	v_add_f32_e32 v183, v183, v63
	v_add_u32_e32 v71, 0x1000, v65
	global_load_dwordx4 v[32:35], v71, s[8:9] offset:256
	v_add_u32_e32 v71, 0x300000, v71
	global_load_dwordx4 v[36:39], v71, s[8:9] offset:256
	v_add_u32_e32 v71, 0x300000, v71
	global_load_dwordx4 v[40:43], v71, s[8:9] offset:256
	v_add_u32_e32 v71, 0x300000, v71
	global_load_dwordx4 v[44:47], v71, s[8:9] offset:256
	v_add_u32_e32 v71, 0x300000, v71
	global_load_dwordx4 v[48:51], v71, s[8:9] offset:256
	v_add_u32_e32 v71, 0x300000, v71
	global_load_dwordx4 v[52:55], v71, s[8:9] offset:256
	v_add_u32_e32 v71, 0x300000, v71
	global_load_dwordx4 v[56:59], v71, s[8:9] offset:256
	v_add_u32_e32 v71, 0x300000, v71
	global_load_dwordx4 v[60:63], v71, s[8:9] offset:256
	s_waitcnt vmcnt(8)
	v_add_f32_e32 v184, v0, v4
	v_add_f32_e32 v185, v1, v5
	v_add_f32_e32 v186, v2, v6
	v_add_f32_e32 v187, v3, v7
	v_add_f32_e32 v184, v184, v8
	v_add_f32_e32 v185, v185, v9
	v_add_f32_e32 v186, v186, v10
	v_add_f32_e32 v187, v187, v11
	v_add_f32_e32 v184, v184, v12
	v_add_f32_e32 v185, v185, v13
	v_add_f32_e32 v186, v186, v14
	v_add_f32_e32 v187, v187, v15
	v_add_f32_e32 v184, v184, v16
	v_add_f32_e32 v185, v185, v17
	v_add_f32_e32 v186, v186, v18
	v_add_f32_e32 v187, v187, v19
	v_add_f32_e32 v184, v184, v20
	v_add_f32_e32 v185, v185, v21
	v_add_f32_e32 v186, v186, v22
	v_add_f32_e32 v187, v187, v23
	v_add_f32_e32 v184, v184, v24
	v_add_f32_e32 v185, v185, v25
	v_add_f32_e32 v186, v186, v26
	v_add_f32_e32 v187, v187, v27
	v_add_f32_e32 v184, v184, v28
	v_add_f32_e32 v185, v185, v29
	v_add_f32_e32 v186, v186, v30
	v_add_f32_e32 v187, v187, v31
	s_waitcnt vmcnt(0)
	v_add_f32_e32 v188, v32, v36
	v_add_f32_e32 v189, v33, v37
	v_add_f32_e32 v190, v34, v38
	v_add_f32_e32 v191, v35, v39
	v_add_f32_e32 v188, v188, v40
	v_add_f32_e32 v189, v189, v41
	v_add_f32_e32 v190, v190, v42
	v_add_f32_e32 v191, v191, v43
	v_add_f32_e32 v188, v188, v44
	v_add_f32_e32 v189, v189, v45
	v_add_f32_e32 v190, v190, v46
	v_add_f32_e32 v191, v191, v47
	v_add_f32_e32 v188, v188, v48
	v_add_f32_e32 v189, v189, v49
	v_add_f32_e32 v190, v190, v50
	v_add_f32_e32 v191, v191, v51
	v_add_f32_e32 v188, v188, v52
	v_add_f32_e32 v189, v189, v53
	v_add_f32_e32 v190, v190, v54
	v_add_f32_e32 v191, v191, v55
	v_add_f32_e32 v188, v188, v56
	v_add_f32_e32 v189, v189, v57
	v_add_f32_e32 v190, v190, v58
	v_add_f32_e32 v191, v191, v59
	v_add_f32_e32 v188, v188, v60
	v_add_f32_e32 v189, v189, v61
	v_add_f32_e32 v190, v190, v62
	v_add_f32_e32 v191, v191, v63
	s_waitcnt lgkmcnt(0)
; __device__ __forceinline__ float fexp2(float x) { return __builtin_amdgcn_exp2f(x); }
; __device__ __forceinline__ void attn_sample_item(const P& p, int wi, int lane) {
;     ...
;     { const float rq = rstd1[TP + srow] * (0.08838834764831845f * LOG2E);
;       const f32x4 q0 = acc1_4(ACC1, srow, 3072 + h * 128 + 8 * li), q1 = acc1_4(ACC1, srow, 3072 + h * 128 + 8 * li + 4);
;       q[0] = q0[0] * rq; q[1] = q0[1] * rq; q[2] = q0[2] * rq; q[3] = q0[3] * rq; q[4] = q1[0] * rq; q[5] = q1[1] * rq; q[6] = q1[2] * rq; q[7] = q1[3] * rq; }
;     if (kg == 0) {
;         const float rs = rstd1[TP + srow];
;         float* ko = p.out + OUT_KN + (size_t)srow * 1024 + h * 128 + 8 * li; float* vo = p.out + OUT_VN + (size_t)srow * 1024 + h * 128 + 8 * li;
;         *(f32x4*)ko = acc1_4(ACC1, srow, 4096 + h * 128 + 8 * li) * rs; *(f32x4*)(ko + 4) = acc1_4(ACC1, srow, 4096 + h * 128 + 8 * li + 4) * rs;
;         *(f32x4*)vo = acc1_4(ACC1, srow, 5120 + h * 128 + 8 * li) * rs; *(f32x4*)(vo + 4) = acc1_4(ACC1, srow, 5120 + h * 128 + 8 * li + 4) * rs;
;     }
;     float m = -1e30f, l = 0.f, acc[8];
; #pragma unroll
;     for (int e = 0; e < 8; ++e) acc[e] = 0.f;
;     const float sl = fexp2(-(float)(h + 1)) * LOG2E;
;     for (int g = 0; g < 3; ++g) {
;         const int d = 1 << (2 * g);
; #pragma unroll 3
;         for (int jj = 0; jj < 33; ++jj) {
;             const int j = 4 * jj + kg; const bool valid = j <= 128; const int jc = valid ? j : 128;
;             const int idx = 2048 + i - d * jc;
;             f32x4 k0, k1, v0, v1;
;             if (idx < 2048) { const size_t off = (((size_t)bs * 2048 + idx) * 8 + h) * 128 + 8 * li;
;                 k0 = __builtin_nontemporal_load((const f32x4*)(p.cache_k + off)); k1 = __builtin_nontemporal_load((const f32x4*)(p.cache_k + off + 4)); v0 = __builtin_nontemporal_load((const f32x4*)(p.cache_v + off)); v1 = __builtin_nontemporal_load((const f32x4*)(p.cache_v + off + 4)); }
;             else { const int nr = bs * 4 + (idx - 2048); const float rsn = rstd1[TP + nr]; const int c0 = 4096 + h * 128 + 8 * li;
;                 k0 = acc1_4(ACC1, nr, c0) * rsn; k1 = acc1_4(ACC1, nr, c0 + 4) * rsn; v0 = acc1_4(ACC1, nr, c0 + 1024) * rsn; v1 = acc1_4(ACC1, nr, c0 + 1028) * rsn; }
	v_mov_b32_e32 v71, s19
	v_mul_f32_e32 v71, 0x3e0293ee, v71
	v_mul_f32_e32 v160, v160, v71
	v_mul_f32_e32 v161, v161, v71
	v_mul_f32_e32 v162, v162, v71
	v_mul_f32_e32 v163, v163, v71
	v_mul_f32_e32 v164, v164, v71
	v_mul_f32_e32 v165, v165, v71
	v_mul_f32_e32 v166, v166, v71
	v_mul_f32_e32 v167, v167, v71
	v_mul_f32_e32 v176, v176, v70
	v_mul_f32_e32 v177, v177, v70
	v_mul_f32_e32 v178, v178, v70
	v_mul_f32_e32 v179, v179, v70
	v_mul_f32_e32 v180, v180, v70
	v_mul_f32_e32 v181, v181, v70
	v_mul_f32_e32 v182, v182, v70
	v_mul_f32_e32 v183, v183, v70
	v_mul_f32_e32 v184, v184, v70
	v_mul_f32_e32 v185, v185, v70
	v_mul_f32_e32 v186, v186, v70
	v_mul_f32_e32 v187, v187, v70
	v_mul_f32_e32 v188, v188, v70
	v_mul_f32_e32 v189, v189, v70
	v_mul_f32_e32 v190, v190, v70
	v_mul_f32_e32 v191, v191, v70
	s_lshl_b32 s43, s17, 12
	v_add_u32_e32 v71, s43, v72
	s_mov_b64 exec, 0xffff
	global_store_dwordx4 v71, v[176:179], s[26:27]
	global_store_dwordx4 v71, v[180:183], s[26:27] offset:256
	global_store_dwordx4 v71, v[184:187], s[28:29]
	global_store_dwordx4 v71, v[188:191], s[28:29] offset:256
	s_mov_b64 exec, -1
	v_cmp_ge_u32_e32 vcc, s15, v73
	s_nop 1
	v_cndmask_b32_e32 v128, v128, v176, vcc
	v_cndmask_b32_e32 v129, v129, v177, vcc
	v_cndmask_b32_e32 v130, v130, v178, vcc
	v_cndmask_b32_e32 v131, v131, v179, vcc
	v_cndmask_b32_e32 v132, v132, v180, vcc
	v_cndmask_b32_e32 v133, v133, v181, vcc
	v_cndmask_b32_e32 v134, v134, v182, vcc
	v_cndmask_b32_e32 v135, v135, v183, vcc
	v_cndmask_b32_e32 v136, v136, v184, vcc
	v_cndmask_b32_e32 v137, v137, v185, vcc
	v_cndmask_b32_e32 v138, v138, v186, vcc
	v_cndmask_b32_e32 v139, v139, v187, vcc
	v_cndmask_b32_e32 v140, v140, v188, vcc
	v_cndmask_b32_e32 v141, v141, v189, vcc
	v_cndmask_b32_e32 v142, v142, v190, vcc
	v_cndmask_b32_e32 v143, v143, v191, vcc
	v_bfe_u32 v183, v230, 4, 2
	v_lshlrev_b32_e32 v195, 12, v183
	v_sub_u32_e32 v195, v203, v195
	s_mov_b32 s42, 0xffffc000
	v_add_u32_e32 v195, s42, v195
	global_load_dwordx4 v[16:19], v195, s[20:21]
	global_load_dwordx4 v[20:23], v195, s[20:21] offset:256
	global_load_dwordx4 v[24:27], v195, s[24:25]
	global_load_dwordx4 v[28:31], v195, s[24:25] offset:256
	v_add_u32_e32 v195, s42, v195
	global_load_dwordx4 v[32:35], v195, s[20:21]
	global_load_dwordx4 v[36:39], v195, s[20:21] offset:256
	global_load_dwordx4 v[40:43], v195, s[24:25]
	global_load_dwordx4 v[44:47], v195, s[24:25] offset:256
	v_add_u32_e32 v195, s42, v195
	global_load_dwordx4 v[48:51], v195, s[20:21]
	global_load_dwordx4 v[52:55], v195, s[20:21] offset:256
	global_load_dwordx4 v[56:59], v195, s[24:25]
	global_load_dwordx4 v[60:63], v195, s[24:25] offset:256
	v_add_u32_e32 v195, s42, v195
	global_load_dwordx4 v[64:67], v195, s[20:21]
	global_load_dwordx4 v[68:71], v195, s[20:21] offset:256
	global_load_dwordx4 v[72:75], v195, s[24:25]
	global_load_dwordx4 v[76:79], v195, s[24:25] offset:256
	v_add_u32_e32 v195, s42, v195
	global_load_dwordx4 v[80:83], v195, s[20:21]
	global_load_dwordx4 v[84:87], v195, s[20:21] offset:256
	global_load_dwordx4 v[88:91], v195, s[24:25]
	global_load_dwordx4 v[92:95], v195, s[24:25] offset:256
	v_add_u32_e32 v195, s42, v195
	global_load_dwordx4 v[96:99], v195, s[20:21]
	global_load_dwordx4 v[100:103], v195, s[20:21] offset:256
	global_load_dwordx4 v[104:107], v195, s[24:25]
	global_load_dwordx4 v[108:111], v195, s[24:25] offset:256
	v_add_u32_e32 v195, s42, v195
	global_load_dwordx4 v[112:115], v195, s[20:21]
	global_load_dwordx4 v[116:119], v195, s[20:21] offset:256
	global_load_dwordx4 v[120:123], v195, s[24:25]
	global_load_dwordx4 v[124:127], v195, s[24:25] offset:256
	v_add_u32_e32 v195, s42, v195
	global_load_dwordx4 v[0:3], v195, s[20:21]
	global_load_dwordx4 v[4:7], v195, s[20:21] offset:256
	global_load_dwordx4 v[8:11], v195, s[24:25]
	global_load_dwordx4 v[12:15], v195, s[24:25] offset:256
	v_lshlrev_b32_e32 v176, 14, v183
	v_sub_u32_e32 v176, v203, v176
	v_add_u32_e32 v176, 0xfff8c000, v176
	v_lshlrev_b32_e32 v177, 16, v183
	v_sub_u32_e32 v177, v203, v177
	v_add_u32_e32 v177, 0xffe30000, v177
	v_add_f32_e32 v182, 0x42040000, v202
	v_mul_f32_e32 v182, v182, v201
	v_mul_f32_e32 v178, 4.0, v182
	v_mul_f32_e32 v179, 16.0, v182
	v_mul_f32_e32 v180, 16.0, v201
	v_mul_f32_e32 v181, 64.0, v201
	v_mul_f32_e32 v196, 4.0, v201
	v_mov_b32_e32 v187, 0
	v_cmp_eq_u32_e32 vcc, 0, v183
	v_mov_b32_e32 v188, 0x3d800000
	s_nop 1
	v_cndmask_b32_e32 v185, v187, v188, vcc
	v_mov_b32_e32 v188, 0x3dcae00d
	v_cndmask_b32_e32 v184, v187, v188, vcc
	v_cmp_eq_u32_e32 vcc, 3, v183
	v_mov_b32_e32 v188, 0x3d800000
	s_nop 1
	v_cndmask_b32_e32 v186, v187, v188, vcc
	s_bitcmp1_b32 s2, 4
	s_cbranch_scc0 .Las_noswap
	v_swap_b32 v176, v177
	v_swap_b32 v178, v179
	v_swap_b32 v180, v181
	v_swap_b32 v186, v187
; __device__ __forceinline__ float fexp2(float x) { return __builtin_amdgcn_exp2f(x); }
; __device__ __forceinline__ void attn_sample_item(const P& p, int wi, int lane) {
;     ...
;     float m = -1e30f, l = 0.f, acc[8];
; #pragma unroll
;     for (int e = 0; e < 8; ++e) acc[e] = 0.f;
;     const float sl = fexp2(-(float)(h + 1)) * LOG2E;
;     for (int g = 0; g < 3; ++g) {
;         const int d = 1 << (2 * g);
; #pragma unroll 3
;         for (int jj = 0; jj < 33; ++jj) {
;             const int j = 4 * jj + kg; const bool valid = j <= 128; const int jc = valid ? j : 128;
;             const int idx = 2048 + i - d * jc;
;             f32x4 k0, k1, v0, v1;
;             if (idx < 2048) { const size_t off = (((size_t)bs * 2048 + idx) * 8 + h) * 128 + 8 * li;
;                 k0 = __builtin_nontemporal_load((const f32x4*)(p.cache_k + off)); k1 = __builtin_nontemporal_load((const f32x4*)(p.cache_k + off + 4)); v0 = __builtin_nontemporal_load((const f32x4*)(p.cache_v + off)); v1 = __builtin_nontemporal_load((const f32x4*)(p.cache_v + off + 4)); }
;             else { const int nr = bs * 4 + (idx - 2048); const float rsn = rstd1[TP + nr]; const int c0 = 4096 + h * 128 + 8 * li;
;                 k0 = acc1_4(ACC1, nr, c0) * rsn; k1 = acc1_4(ACC1, nr, c0 + 4) * rsn; v0 = acc1_4(ACC1, nr, c0 + 1024) * rsn; v1 = acc1_4(ACC1, nr, c0 + 1028) * rsn; }
;             float dot = (q[0] * k0[0] + q[1] * k0[1]) + (q[2] * k0[2] + q[3] * k0[3]) + (q[4] * k1[0] + q[5] * k1[1]) + (q[6] * k1[2] + q[7] * k1[3]);
;             dot += __shfl_xor(dot, 1); dot += __shfl_xor(dot, 2); dot += __shfl_xor(dot, 4); dot += __shfl_xor(dot, 8);
;             const float s = valid ? dot - sl * (float)(d * j) : -INFINITY;
;             const float mn = fmaxf(m, s), sc = fexp2(m - mn), pe = fexp2(s - mn);
;             l = l * sc + pe;
;             acc[0] = acc[0] * sc + pe * v0[0]; acc[1] = acc[1] * sc + pe * v0[1]; acc[2] = acc[2] * sc + pe * v0[2]; acc[3] = acc[3] * sc + pe * v0[3];
;             acc[4] = acc[4] * sc + pe * v1[0]; acc[5] = acc[5] * sc + pe * v1[1]; acc[6] = acc[6] * sc + pe * v1[2]; acc[7] = acc[7] * sc + pe * v1[3];
;             m = mn;
;         }
.Las_noswap:
	v_mov_b32_e32 v192, 0xf149f2ca
	v_mov_b32_e32 v193, 0
	v_mov_b32_e32 v168, 0
	v_mov_b32_e32 v169, 0
	v_mov_b32_e32 v170, 0
	v_mov_b32_e32 v171, 0
	v_mov_b32_e32 v172, 0
	v_mov_b32_e32 v173, 0
	v_mov_b32_e32 v174, 0
	v_mov_b32_e32 v175, 0
	v_mul_f32_e32 v194, v201, v202
	v_mov_b32_e32 v182, 0x3dcae00d
	v_cmp_eq_u32_e32 vcc, 0, v183
	s_nop 1
	v_cndmask_b32_e32 v194, v194, v182, vcc
	v_fma_f32 v197, v160, v128, v194
	v_fmac_f32_e32 v197, v161, v129
	v_fmac_f32_e32 v197, v162, v130
	v_fmac_f32_e32 v197, v163, v131
	v_fmac_f32_e32 v197, v164, v132
	v_fmac_f32_e32 v197, v165, v133
	v_fmac_f32_e32 v197, v166, v134
	v_fmac_f32_e32 v197, v167, v135
	s_nop 1
	v_add_f32_dpp v197, v197, v197 row_ror:8 row_mask:0xf bank_mask:0xf
	s_nop 1
	v_add_f32_dpp v197, v197, v197 row_ror:4 row_mask:0xf bank_mask:0xf
	s_nop 1
	v_add_f32_dpp v197, v197, v197 row_ror:2 row_mask:0xf bank_mask:0xf
	s_nop 1
	v_add_f32_dpp v197, v197, v197 row_ror:1 row_mask:0xf bank_mask:0xf
	v_max_f32_e32 v198, v192, v197
	v_sub_f32_e32 v199, v192, v198
	v_sub_f32_e32 v200, v197, v198
	v_exp_f32_e32 v199, v199
	v_exp_f32_e32 v200, v200
	v_mov_b32_e32 v192, v198
	v_fma_f32 v193, v193, v199, v200
	v_mul_f32_e32 v168, v168, v199
	v_mul_f32_e32 v169, v169, v199
	v_mul_f32_e32 v170, v170, v199
	v_mul_f32_e32 v171, v171, v199
	v_mul_f32_e32 v172, v172, v199
	v_mul_f32_e32 v173, v173, v199
	v_mul_f32_e32 v174, v174, v199
	v_mul_f32_e32 v175, v175, v199
	v_fmac_f32_e32 v168, v200, v136
	v_fmac_f32_e32 v169, v200, v137
	v_fmac_f32_e32 v170, v200, v138
	v_fmac_f32_e32 v171, v200, v139
	v_fmac_f32_e32 v172, v200, v140
	v_fmac_f32_e32 v173, v200, v141
	v_fmac_f32_e32 v174, v200, v142
	v_fmac_f32_e32 v175, v200, v143
	v_mul_f32_e32 v194, 0x43000000, v201
	v_add_f32_e32 v194, v194, v184
	v_mov_b32_e32 v182, 0xff800000
	v_cndmask_b32_e32 v194, v182, v194, vcc
	v_fma_f32 v197, v160, v144, v194
	v_fmac_f32_e32 v197, v161, v145
	v_fmac_f32_e32 v197, v162, v146
	v_fmac_f32_e32 v197, v163, v147
	v_fmac_f32_e32 v197, v164, v148
	v_fmac_f32_e32 v197, v165, v149
	v_fmac_f32_e32 v197, v166, v150
	v_fmac_f32_e32 v197, v167, v151
	s_nop 1
	v_add_f32_dpp v197, v197, v197 row_ror:8 row_mask:0xf bank_mask:0xf
	s_nop 1
	v_add_f32_dpp v197, v197, v197 row_ror:4 row_mask:0xf bank_mask:0xf
	s_nop 1
	v_add_f32_dpp v197, v197, v197 row_ror:2 row_mask:0xf bank_mask:0xf
	s_nop 1
	v_add_f32_dpp v197, v197, v197 row_ror:1 row_mask:0xf bank_mask:0xf
	v_max_f32_e32 v198, v192, v197
	v_sub_f32_e32 v199, v192, v198
	v_sub_f32_e32 v200, v197, v198
	v_exp_f32_e32 v199, v199
	v_exp_f32_e32 v200, v200
	v_mov_b32_e32 v192, v198
	v_fma_f32 v193, v193, v199, v200
	v_mul_f32_e32 v168, v168, v199
	v_mul_f32_e32 v169, v169, v199
	v_mul_f32_e32 v170, v170, v199
	v_mul_f32_e32 v171, v171, v199
	v_mul_f32_e32 v172, v172, v199
	v_mul_f32_e32 v173, v173, v199
	v_mul_f32_e32 v174, v174, v199
	v_mul_f32_e32 v175, v175, v199
	v_fmac_f32_e32 v168, v200, v152
	v_fmac_f32_e32 v169, v200, v153
	v_fmac_f32_e32 v170, v200, v154
	v_fmac_f32_e32 v171, v200, v155
	v_fmac_f32_e32 v172, v200, v156
	v_fmac_f32_e32 v173, v200, v157
	v_fmac_f32_e32 v174, v200, v158
	v_fmac_f32_e32 v175, v200, v159
	v_add_f32_e32 v194, 4.0, v202
	v_mul_f32_e32 v194, v194, v201
	s_mov_b32 s33, 0
	s_branch .Las_slot1

; __device__ __forceinline__ float fexp2(float x) { return __builtin_amdgcn_exp2f(x); }
; __device__ __forceinline__ void attn_sample_item(const P& p, int wi, int lane) {
;     ...
;         for (int jj = 0; jj < 33; ++jj) {
;             const int j = 4 * jj + kg; const bool valid = j <= 128; const int jc = valid ? j : 128;
;             const int idx = 2048 + i - d * jc;
;             f32x4 k0, k1, v0, v1;
;             if (idx < 2048) { const size_t off = (((size_t)bs * 2048 + idx) * 8 + h) * 128 + 8 * li;
;                 k0 = __builtin_nontemporal_load((const f32x4*)(p.cache_k + off)); k1 = __builtin_nontemporal_load((const f32x4*)(p.cache_k + off + 4)); v0 = __builtin_nontemporal_load((const f32x4*)(p.cache_v + off)); v1 = __builtin_nontemporal_load((const f32x4*)(p.cache_v + off + 4)); }
;             else { const int nr = bs * 4 + (idx - 2048); const float rsn = rstd1[TP + nr]; const int c0 = 4096 + h * 128 + 8 * li;
;                 k0 = acc1_4(ACC1, nr, c0) * rsn; k1 = acc1_4(ACC1, nr, c0 + 4) * rsn; v0 = acc1_4(ACC1, nr, c0 + 1024) * rsn; v1 = acc1_4(ACC1, nr, c0 + 1028) * rsn; }
;             float dot = (q[0] * k0[0] + q[1] * k0[1]) + (q[2] * k0[2] + q[3] * k0[3]) + (q[4] * k1[0] + q[5] * k1[1]) + (q[6] * k1[2] + q[7] * k1[3]);
;             dot += __shfl_xor(dot, 1); dot += __shfl_xor(dot, 2); dot += __shfl_xor(dot, 4); dot += __shfl_xor(dot, 8);
;             const float s = valid ? dot - sl * (float)(d * j) : -INFINITY;
;             const float mn = fmaxf(m, s), sc = fexp2(m - mn), pe = fexp2(s - mn);
;             l = l * sc + pe;
;             acc[0] = acc[0] * sc + pe * v0[0]; acc[1] = acc[1] * sc + pe * v0[1]; acc[2] = acc[2] * sc + pe * v0[2]; acc[3] = acc[3] * sc + pe * v0[3];
;             acc[4] = acc[4] * sc + pe * v1[0]; acc[5] = acc[5] * sc + pe * v1[1]; acc[6] = acc[6] * sc + pe * v1[2]; acc[7] = acc[7] * sc + pe * v1[3];
;             m = mn;
;         }
.Las_sw1A:
	s_cmp_eq_u32 s33, 6
	s_cbranch_scc0 .Las_sw2A
	v_mov_b32_e32 v195, v177
	s_mov_b32 s42, 0xfffc0000
	s_bitcmp1_b32 s2, 4
	s_cbranch_scc0 .Las_sw2A
	s_mov_b32 s42, 0xffff0000
.Las_sw2A:
	s_cmp_eq_u32 s33, 4
	s_cbranch_scc0 .Las_sw3A
	v_mov_b32_e32 v194, v178
	v_mov_b32_e32 v196, v180
	v_mov_b32_e32 v184, v186
	v_mov_b32_e32 v185, v186
.Las_sw3A:
	s_cmp_eq_u32 s33, 7
	s_cbranch_scc0 .Las_sw4A
	v_mov_b32_e32 v194, v179
	v_mov_b32_e32 v196, v181
	v_mov_b32_e32 v184, v187
	v_mov_b32_e32 v185, v187
.Las_sw4A:
	s_waitcnt vmcnt(28)
	v_add_f32_e32 v188, v194, v184
	v_fma_f32 v197, v160, v0, v188
	v_fmac_f32_e32 v197, v161, v1
	v_fmac_f32_e32 v197, v162, v2
	v_fmac_f32_e32 v197, v163, v3
	v_fmac_f32_e32 v197, v164, v4
	v_fmac_f32_e32 v197, v165, v5
	v_fmac_f32_e32 v197, v166, v6
	v_fmac_f32_e32 v197, v167, v7
	s_nop 1
	v_add_f32_dpp v197, v197, v197 row_ror:8 row_mask:0xf bank_mask:0xf
	s_nop 1
	v_add_f32_dpp v197, v197, v197 row_ror:4 row_mask:0xf bank_mask:0xf
	s_nop 1
	v_add_f32_dpp v197, v197, v197 row_ror:2 row_mask:0xf bank_mask:0xf
	s_nop 1
	v_add_f32_dpp v197, v197, v197 row_ror:1 row_mask:0xf bank_mask:0xf
	v_max_f32_e32 v198, v192, v197
	v_sub_f32_e32 v199, v192, v198
	v_sub_f32_e32 v200, v197, v198
	v_exp_f32_e32 v199, v199
	v_exp_f32_e32 v200, v200
	v_mov_b32_e32 v192, v198
	v_fma_f32 v193, v193, v199, v200
	v_mul_f32_e32 v168, v168, v199
	v_mul_f32_e32 v169, v169, v199
	v_mul_f32_e32 v170, v170, v199
	v_mul_f32_e32 v171, v171, v199
	v_mul_f32_e32 v172, v172, v199
	v_mul_f32_e32 v173, v173, v199
	v_mul_f32_e32 v174, v174, v199
	v_mul_f32_e32 v175, v175, v199
	v_fmac_f32_e32 v168, v200, v8
	v_fmac_f32_e32 v169, v200, v9
	v_fmac_f32_e32 v170, v200, v10
	v_fmac_f32_e32 v171, v200, v11
	v_fmac_f32_e32 v172, v200, v12
	v_fmac_f32_e32 v173, v200, v13
	v_fmac_f32_e32 v174, v200, v14
	v_fmac_f32_e32 v175, v200, v15
	v_add_f32_e32 v194, v194, v196
	v_add_u32_e32 v195, s42, v195
	global_load_dwordx4 v[0:3], v195, s[20:21]
	global_load_dwordx4 v[4:7], v195, s[20:21] offset:256
	global_load_dwordx4 v[8:11], v195, s[24:25]
	global_load_dwordx4 v[12:15], v195, s[24:25] offset:256
.Las_slot1:
	s_waitcnt vmcnt(28)
	v_add_f32_e32 v188, v194, v185
	v_fma_f32 v197, v160, v16, v188
	v_fmac_f32_e32 v197, v161, v17
	v_fmac_f32_e32 v197, v162, v18
	v_fmac_f32_e32 v197, v163, v19
	v_fmac_f32_e32 v197, v164, v20
	v_fmac_f32_e32 v197, v165, v21
	v_fmac_f32_e32 v197, v166, v22
	v_fmac_f32_e32 v197, v167, v23
	s_nop 1
	v_add_f32_dpp v197, v197, v197 row_ror:8 row_mask:0xf bank_mask:0xf
	s_nop 1
	v_add_f32_dpp v197, v197, v197 row_ror:4 row_mask:0xf bank_mask:0xf
	s_nop 1
	v_add_f32_dpp v197, v197, v197 row_ror:2 row_mask:0xf bank_mask:0xf
	s_nop 1
	v_add_f32_dpp v197, v197, v197 row_ror:1 row_mask:0xf bank_mask:0xf
	v_max_f32_e32 v198, v192, v197
	v_sub_f32_e32 v199, v192, v198
	v_sub_f32_e32 v200, v197, v198
	v_exp_f32_e32 v199, v199
	v_exp_f32_e32 v200, v200
	v_mov_b32_e32 v192, v198
	v_fma_f32 v193, v193, v199, v200
	v_mul_f32_e32 v168, v168, v199
	v_mul_f32_e32 v169, v169, v199
	v_mul_f32_e32 v170, v170, v199
	v_mul_f32_e32 v171, v171, v199
	v_mul_f32_e32 v172, v172, v199
	v_mul_f32_e32 v173, v173, v199
	v_mul_f32_e32 v174, v174, v199
	v_mul_f32_e32 v175, v175, v199
	v_fmac_f32_e32 v168, v200, v24
	v_fmac_f32_e32 v169, v200, v25
	v_fmac_f32_e32 v170, v200, v26
	v_fmac_f32_e32 v171, v200, v27
	v_fmac_f32_e32 v172, v200, v28
	v_fmac_f32_e32 v173, v200, v29
	v_fmac_f32_e32 v174, v200, v30
	v_fmac_f32_e32 v175, v200, v31
	v_add_f32_e32 v194, v194, v196
	v_add_u32_e32 v195, s42, v195
	global_load_dwordx4 v[16:19], v195, s[20:21]
	global_load_dwordx4 v[20:23], v195, s[20:21] offset:256
	global_load_dwordx4 v[24:27], v195, s[24:25]
	global_load_dwordx4 v[28:31], v195, s[24:25] offset:256
	s_waitcnt vmcnt(28)
	v_add_f32_e32 v188, v194, v185
	v_fma_f32 v197, v160, v32, v188
	v_fmac_f32_e32 v197, v161, v33
	v_fmac_f32_e32 v197, v162, v34
	v_fmac_f32_e32 v197, v163, v35
	v_fmac_f32_e32 v197, v164, v36
	v_fmac_f32_e32 v197, v165, v37
	v_fmac_f32_e32 v197, v166, v38
	v_fmac_f32_e32 v197, v167, v39
	s_nop 1
	v_add_f32_dpp v197, v197, v197 row_ror:8 row_mask:0xf bank_mask:0xf
	s_nop 1
	v_add_f32_dpp v197, v197, v197 row_ror:4 row_mask:0xf bank_mask:0xf
	s_nop 1
	v_add_f32_dpp v197, v197, v197 row_ror:2 row_mask:0xf bank_mask:0xf
	s_nop 1
	v_add_f32_dpp v197, v197, v197 row_ror:1 row_mask:0xf bank_mask:0xf
	v_max_f32_e32 v198, v192, v197
	v_sub_f32_e32 v199, v192, v198
	v_sub_f32_e32 v200, v197, v198
	v_exp_f32_e32 v199, v199
	v_exp_f32_e32 v200, v200
	v_mov_b32_e32 v192, v198
	v_fma_f32 v193, v193, v199, v200
	v_mul_f32_e32 v168, v168, v199
	v_mul_f32_e32 v169, v169, v199
	v_mul_f32_e32 v170, v170, v199
	v_mul_f32_e32 v171, v171, v199
	v_mul_f32_e32 v172, v172, v199
	v_mul_f32_e32 v173, v173, v199
	v_mul_f32_e32 v174, v174, v199
	v_mul_f32_e32 v175, v175, v199
	v_fmac_f32_e32 v168, v200, v40
	v_fmac_f32_e32 v169, v200, v41
	v_fmac_f32_e32 v170, v200, v42
	v_fmac_f32_e32 v171, v200, v43
	v_fmac_f32_e32 v172, v200, v44
	v_fmac_f32_e32 v173, v200, v45
	v_fmac_f32_e32 v174, v200, v46
	v_fmac_f32_e32 v175, v200, v47
	v_add_f32_e32 v194, v194, v196
	v_add_u32_e32 v195, s42, v195
	global_load_dwordx4 v[32:35], v195, s[20:21]
	global_load_dwordx4 v[36:39], v195, s[20:21] offset:256
	global_load_dwordx4 v[40:43], v195, s[24:25]
	global_load_dwordx4 v[44:47], v195, s[24:25] offset:256
	s_waitcnt vmcnt(28)
; __device__ __forceinline__ float fexp2(float x) { return __builtin_amdgcn_exp2f(x); }
; __device__ __forceinline__ void attn_sample_item(const P& p, int wi, int lane) {
;     ...
;         for (int jj = 0; jj < 33; ++jj) {
;             const int j = 4 * jj + kg; const bool valid = j <= 128; const int jc = valid ? j : 128;
;             const int idx = 2048 + i - d * jc;
;             f32x4 k0, k1, v0, v1;
;             if (idx < 2048) { const size_t off = (((size_t)bs * 2048 + idx) * 8 + h) * 128 + 8 * li;
;                 k0 = __builtin_nontemporal_load((const f32x4*)(p.cache_k + off)); k1 = __builtin_nontemporal_load((const f32x4*)(p.cache_k + off + 4)); v0 = __builtin_nontemporal_load((const f32x4*)(p.cache_v + off)); v1 = __builtin_nontemporal_load((const f32x4*)(p.cache_v + off + 4)); }
;             else { const int nr = bs * 4 + (idx - 2048); const float rsn = rstd1[TP + nr]; const int c0 = 4096 + h * 128 + 8 * li;
;                 k0 = acc1_4(ACC1, nr, c0) * rsn; k1 = acc1_4(ACC1, nr, c0 + 4) * rsn; v0 = acc1_4(ACC1, nr, c0 + 1024) * rsn; v1 = acc1_4(ACC1, nr, c0 + 1028) * rsn; }
;             float dot = (q[0] * k0[0] + q[1] * k0[1]) + (q[2] * k0[2] + q[3] * k0[3]) + (q[4] * k1[0] + q[5] * k1[1]) + (q[6] * k1[2] + q[7] * k1[3]);
;             dot += __shfl_xor(dot, 1); dot += __shfl_xor(dot, 2); dot += __shfl_xor(dot, 4); dot += __shfl_xor(dot, 8);
;             const float s = valid ? dot - sl * (float)(d * j) : -INFINITY;
;             const float mn = fmaxf(m, s), sc = fexp2(m - mn), pe = fexp2(s - mn);
;             l = l * sc + pe;
;             acc[0] = acc[0] * sc + pe * v0[0]; acc[1] = acc[1] * sc + pe * v0[1]; acc[2] = acc[2] * sc + pe * v0[2]; acc[3] = acc[3] * sc + pe * v0[3];
;             acc[4] = acc[4] * sc + pe * v1[0]; acc[5] = acc[5] * sc + pe * v1[1]; acc[6] = acc[6] * sc + pe * v1[2]; acc[7] = acc[7] * sc + pe * v1[3];
;             m = mn;
;         }
	v_add_f32_e32 v188, v194, v185
	v_fma_f32 v197, v160, v48, v188
	v_fmac_f32_e32 v197, v161, v49
	v_fmac_f32_e32 v197, v162, v50
	v_fmac_f32_e32 v197, v163, v51
	v_fmac_f32_e32 v197, v164, v52
	v_fmac_f32_e32 v197, v165, v53
	v_fmac_f32_e32 v197, v166, v54
	v_fmac_f32_e32 v197, v167, v55
	s_nop 1
	v_add_f32_dpp v197, v197, v197 row_ror:8 row_mask:0xf bank_mask:0xf
	s_nop 1
	v_add_f32_dpp v197, v197, v197 row_ror:4 row_mask:0xf bank_mask:0xf
	s_nop 1
	v_add_f32_dpp v197, v197, v197 row_ror:2 row_mask:0xf bank_mask:0xf
	s_nop 1
	v_add_f32_dpp v197, v197, v197 row_ror:1 row_mask:0xf bank_mask:0xf
	v_max_f32_e32 v198, v192, v197
	v_sub_f32_e32 v199, v192, v198
	v_sub_f32_e32 v200, v197, v198
	v_exp_f32_e32 v199, v199
	v_exp_f32_e32 v200, v200
	v_mov_b32_e32 v192, v198
	v_fma_f32 v193, v193, v199, v200
	v_mul_f32_e32 v168, v168, v199
	v_mul_f32_e32 v169, v169, v199
	v_mul_f32_e32 v170, v170, v199
	v_mul_f32_e32 v171, v171, v199
	v_mul_f32_e32 v172, v172, v199
	v_mul_f32_e32 v173, v173, v199
	v_mul_f32_e32 v174, v174, v199
	v_mul_f32_e32 v175, v175, v199
	v_fmac_f32_e32 v168, v200, v56
	v_fmac_f32_e32 v169, v200, v57
	v_fmac_f32_e32 v170, v200, v58
	v_fmac_f32_e32 v171, v200, v59
	v_fmac_f32_e32 v172, v200, v60
	v_fmac_f32_e32 v173, v200, v61
	v_fmac_f32_e32 v174, v200, v62
	v_fmac_f32_e32 v175, v200, v63
	v_add_f32_e32 v194, v194, v196
	v_add_u32_e32 v195, s42, v195
	global_load_dwordx4 v[48:51], v195, s[20:21]
	global_load_dwordx4 v[52:55], v195, s[20:21] offset:256
	global_load_dwordx4 v[56:59], v195, s[24:25]
	global_load_dwordx4 v[60:63], v195, s[24:25] offset:256
	s_waitcnt vmcnt(28)
	v_add_f32_e32 v188, v194, v184
	v_fma_f32 v197, v160, v64, v188
	v_fmac_f32_e32 v197, v161, v65
	v_fmac_f32_e32 v197, v162, v66
	v_fmac_f32_e32 v197, v163, v67
	v_fmac_f32_e32 v197, v164, v68
	v_fmac_f32_e32 v197, v165, v69
	v_fmac_f32_e32 v197, v166, v70
	v_fmac_f32_e32 v197, v167, v71
	s_nop 1
	v_add_f32_dpp v197, v197, v197 row_ror:8 row_mask:0xf bank_mask:0xf
	s_nop 1
	v_add_f32_dpp v197, v197, v197 row_ror:4 row_mask:0xf bank_mask:0xf
	s_nop 1
	v_add_f32_dpp v197, v197, v197 row_ror:2 row_mask:0xf bank_mask:0xf
	s_nop 1
	v_add_f32_dpp v197, v197, v197 row_ror:1 row_mask:0xf bank_mask:0xf
	v_max_f32_e32 v198, v192, v197
	v_sub_f32_e32 v199, v192, v198
	v_sub_f32_e32 v200, v197, v198
	v_exp_f32_e32 v199, v199
	v_exp_f32_e32 v200, v200
	v_mov_b32_e32 v192, v198
	v_fma_f32 v193, v193, v199, v200
	v_mul_f32_e32 v168, v168, v199
	v_mul_f32_e32 v169, v169, v199
	v_mul_f32_e32 v170, v170, v199
	v_mul_f32_e32 v171, v171, v199
	v_mul_f32_e32 v172, v172, v199
	v_mul_f32_e32 v173, v173, v199
	v_mul_f32_e32 v174, v174, v199
	v_mul_f32_e32 v175, v175, v199
	v_fmac_f32_e32 v168, v200, v72
	v_fmac_f32_e32 v169, v200, v73
	v_fmac_f32_e32 v170, v200, v74
	v_fmac_f32_e32 v171, v200, v75
	v_fmac_f32_e32 v172, v200, v76
	v_fmac_f32_e32 v173, v200, v77
	v_fmac_f32_e32 v174, v200, v78
	v_fmac_f32_e32 v175, v200, v79
	v_add_f32_e32 v194, v194, v196
	v_add_u32_e32 v195, s42, v195
	global_load_dwordx4 v[64:67], v195, s[20:21]
	global_load_dwordx4 v[68:71], v195, s[20:21] offset:256
	global_load_dwordx4 v[72:75], v195, s[24:25]
	global_load_dwordx4 v[76:79], v195, s[24:25] offset:256
	s_waitcnt vmcnt(28)
	v_add_f32_e32 v188, v194, v185
	v_fma_f32 v197, v160, v80, v188
	v_fmac_f32_e32 v197, v161, v81
	v_fmac_f32_e32 v197, v162, v82
	v_fmac_f32_e32 v197, v163, v83
	v_fmac_f32_e32 v197, v164, v84
	v_fmac_f32_e32 v197, v165, v85
	v_fmac_f32_e32 v197, v166, v86
	v_fmac_f32_e32 v197, v167, v87
	s_nop 1
	v_add_f32_dpp v197, v197, v197 row_ror:8 row_mask:0xf bank_mask:0xf
	s_nop 1
	v_add_f32_dpp v197, v197, v197 row_ror:4 row_mask:0xf bank_mask:0xf
	s_nop 1
	v_add_f32_dpp v197, v197, v197 row_ror:2 row_mask:0xf bank_mask:0xf
	s_nop 1
	v_add_f32_dpp v197, v197, v197 row_ror:1 row_mask:0xf bank_mask:0xf
	v_max_f32_e32 v198, v192, v197
	v_sub_f32_e32 v199, v192, v198
	v_sub_f32_e32 v200, v197, v198
	v_exp_f32_e32 v199, v199
	v_exp_f32_e32 v200, v200
	v_mov_b32_e32 v192, v198
	v_fma_f32 v193, v193, v199, v200
	v_mul_f32_e32 v168, v168, v199
	v_mul_f32_e32 v169, v169, v199
	v_mul_f32_e32 v170, v170, v199
	v_mul_f32_e32 v171, v171, v199
	v_mul_f32_e32 v172, v172, v199
	v_mul_f32_e32 v173, v173, v199
	v_mul_f32_e32 v174, v174, v199
	v_mul_f32_e32 v175, v175, v199
	v_fmac_f32_e32 v168, v200, v88
	v_fmac_f32_e32 v169, v200, v89
	v_fmac_f32_e32 v170, v200, v90
	v_fmac_f32_e32 v171, v200, v91
	v_fmac_f32_e32 v172, v200, v92
	v_fmac_f32_e32 v173, v200, v93
	v_fmac_f32_e32 v174, v200, v94
	v_fmac_f32_e32 v175, v200, v95
	v_add_f32_e32 v194, v194, v196
	v_add_u32_e32 v195, s42, v195
	global_load_dwordx4 v[80:83], v195, s[20:21]
	global_load_dwordx4 v[84:87], v195, s[20:21] offset:256
	global_load_dwordx4 v[88:91], v195, s[24:25]
	global_load_dwordx4 v[92:95], v195, s[24:25] offset:256
	s_waitcnt vmcnt(28)
; __device__ __forceinline__ float fexp2(float x) { return __builtin_amdgcn_exp2f(x); }
; __device__ __forceinline__ void attn_sample_item(const P& p, int wi, int lane) {
;     ...
;         for (int jj = 0; jj < 33; ++jj) {
;             const int j = 4 * jj + kg; const bool valid = j <= 128; const int jc = valid ? j : 128;
;             const int idx = 2048 + i - d * jc;
;             f32x4 k0, k1, v0, v1;
;             if (idx < 2048) { const size_t off = (((size_t)bs * 2048 + idx) * 8 + h) * 128 + 8 * li;
;                 k0 = __builtin_nontemporal_load((const f32x4*)(p.cache_k + off)); k1 = __builtin_nontemporal_load((const f32x4*)(p.cache_k + off + 4)); v0 = __builtin_nontemporal_load((const f32x4*)(p.cache_v + off)); v1 = __builtin_nontemporal_load((const f32x4*)(p.cache_v + off + 4)); }
;             else { const int nr = bs * 4 + (idx - 2048); const float rsn = rstd1[TP + nr]; const int c0 = 4096 + h * 128 + 8 * li;
;                 k0 = acc1_4(ACC1, nr, c0) * rsn; k1 = acc1_4(ACC1, nr, c0 + 4) * rsn; v0 = acc1_4(ACC1, nr, c0 + 1024) * rsn; v1 = acc1_4(ACC1, nr, c0 + 1028) * rsn; }
;             float dot = (q[0] * k0[0] + q[1] * k0[1]) + (q[2] * k0[2] + q[3] * k0[3]) + (q[4] * k1[0] + q[5] * k1[1]) + (q[6] * k1[2] + q[7] * k1[3]);
;             dot += __shfl_xor(dot, 1); dot += __shfl_xor(dot, 2); dot += __shfl_xor(dot, 4); dot += __shfl_xor(dot, 8);
;             const float s = valid ? dot - sl * (float)(d * j) : -INFINITY;
;             const float mn = fmaxf(m, s), sc = fexp2(m - mn), pe = fexp2(s - mn);
;             l = l * sc + pe;
;             acc[0] = acc[0] * sc + pe * v0[0]; acc[1] = acc[1] * sc + pe * v0[1]; acc[2] = acc[2] * sc + pe * v0[2]; acc[3] = acc[3] * sc + pe * v0[3];
;             acc[4] = acc[4] * sc + pe * v1[0]; acc[5] = acc[5] * sc + pe * v1[1]; acc[6] = acc[6] * sc + pe * v1[2]; acc[7] = acc[7] * sc + pe * v1[3];
;             m = mn;
;         }
	v_add_f32_e32 v188, v194, v185
	v_fma_f32 v197, v160, v96, v188
	v_fmac_f32_e32 v197, v161, v97
	v_fmac_f32_e32 v197, v162, v98
	v_fmac_f32_e32 v197, v163, v99
	v_fmac_f32_e32 v197, v164, v100
	v_fmac_f32_e32 v197, v165, v101
	v_fmac_f32_e32 v197, v166, v102
	v_fmac_f32_e32 v197, v167, v103
	s_nop 1
	v_add_f32_dpp v197, v197, v197 row_ror:8 row_mask:0xf bank_mask:0xf
	s_nop 1
	v_add_f32_dpp v197, v197, v197 row_ror:4 row_mask:0xf bank_mask:0xf
	s_nop 1
	v_add_f32_dpp v197, v197, v197 row_ror:2 row_mask:0xf bank_mask:0xf
	s_nop 1
	v_add_f32_dpp v197, v197, v197 row_ror:1 row_mask:0xf bank_mask:0xf
	v_max_f32_e32 v198, v192, v197
	v_sub_f32_e32 v199, v192, v198
	v_sub_f32_e32 v200, v197, v198
	v_exp_f32_e32 v199, v199
	v_exp_f32_e32 v200, v200
	v_mov_b32_e32 v192, v198
	v_fma_f32 v193, v193, v199, v200
	v_mul_f32_e32 v168, v168, v199
	v_mul_f32_e32 v169, v169, v199
	v_mul_f32_e32 v170, v170, v199
	v_mul_f32_e32 v171, v171, v199
	v_mul_f32_e32 v172, v172, v199
	v_mul_f32_e32 v173, v173, v199
	v_mul_f32_e32 v174, v174, v199
	v_mul_f32_e32 v175, v175, v199
	v_fmac_f32_e32 v168, v200, v104
	v_fmac_f32_e32 v169, v200, v105
	v_fmac_f32_e32 v170, v200, v106
	v_fmac_f32_e32 v171, v200, v107
	v_fmac_f32_e32 v172, v200, v108
	v_fmac_f32_e32 v173, v200, v109
	v_fmac_f32_e32 v174, v200, v110
	v_fmac_f32_e32 v175, v200, v111
	v_add_f32_e32 v194, v194, v196
	v_add_u32_e32 v195, s42, v195
	global_load_dwordx4 v[96:99], v195, s[20:21]
	global_load_dwordx4 v[100:103], v195, s[20:21] offset:256
	global_load_dwordx4 v[104:107], v195, s[24:25]
	global_load_dwordx4 v[108:111], v195, s[24:25] offset:256
	s_waitcnt vmcnt(28)
	v_add_f32_e32 v188, v194, v185
	v_fma_f32 v197, v160, v112, v188
	v_fmac_f32_e32 v197, v161, v113
	v_fmac_f32_e32 v197, v162, v114
	v_fmac_f32_e32 v197, v163, v115
	v_fmac_f32_e32 v197, v164, v116
	v_fmac_f32_e32 v197, v165, v117
	v_fmac_f32_e32 v197, v166, v118
	v_fmac_f32_e32 v197, v167, v119
	s_nop 1
	v_add_f32_dpp v197, v197, v197 row_ror:8 row_mask:0xf bank_mask:0xf
	s_nop 1
	v_add_f32_dpp v197, v197, v197 row_ror:4 row_mask:0xf bank_mask:0xf
	s_nop 1
	v_add_f32_dpp v197, v197, v197 row_ror:2 row_mask:0xf bank_mask:0xf
	s_nop 1
	v_add_f32_dpp v197, v197, v197 row_ror:1 row_mask:0xf bank_mask:0xf
	v_max_f32_e32 v198, v192, v197
	v_sub_f32_e32 v199, v192, v198
	v_sub_f32_e32 v200, v197, v198
	v_exp_f32_e32 v199, v199
	v_exp_f32_e32 v200, v200
	v_mov_b32_e32 v192, v198
	v_fma_f32 v193, v193, v199, v200
	v_mul_f32_e32 v168, v168, v199
	v_mul_f32_e32 v169, v169, v199
	v_mul_f32_e32 v170, v170, v199
	v_mul_f32_e32 v171, v171, v199
	v_mul_f32_e32 v172, v172, v199
	v_mul_f32_e32 v173, v173, v199
	v_mul_f32_e32 v174, v174, v199
	v_mul_f32_e32 v175, v175, v199
	v_fmac_f32_e32 v168, v200, v120
	v_fmac_f32_e32 v169, v200, v121
	v_fmac_f32_e32 v170, v200, v122
	v_fmac_f32_e32 v171, v200, v123
	v_fmac_f32_e32 v172, v200, v124
	v_fmac_f32_e32 v173, v200, v125
	v_fmac_f32_e32 v174, v200, v126
	v_fmac_f32_e32 v175, v200, v127
	v_add_f32_e32 v194, v194, v196
	v_add_u32_e32 v195, s42, v195
	global_load_dwordx4 v[112:115], v195, s[20:21]
	global_load_dwordx4 v[116:119], v195, s[20:21] offset:256
	global_load_dwordx4 v[120:123], v195, s[24:25]
	global_load_dwordx4 v[124:127], v195, s[24:25] offset:256
	s_add_u32 s33, s33, 1
	s_cmp_lt_u32 s33, 3
	s_cbranch_scc1 .Las_tripA

; __device__ __forceinline__ float fexp2(float x) { return __builtin_amdgcn_exp2f(x); }
; __device__ __forceinline__ void attn_sample_item(const P& p, int wi, int lane) {
;     ...
;         for (int jj = 0; jj < 33; ++jj) {
;             const int j = 4 * jj + kg; const bool valid = j <= 128; const int jc = valid ? j : 128;
;             const int idx = 2048 + i - d * jc;
;             f32x4 k0, k1, v0, v1;
;             if (idx < 2048) { const size_t off = (((size_t)bs * 2048 + idx) * 8 + h) * 128 + 8 * li;
;                 k0 = __builtin_nontemporal_load((const f32x4*)(p.cache_k + off)); k1 = __builtin_nontemporal_load((const f32x4*)(p.cache_k + off + 4)); v0 = __builtin_nontemporal_load((const f32x4*)(p.cache_v + off)); v1 = __builtin_nontemporal_load((const f32x4*)(p.cache_v + off + 4)); }
;             else { const int nr = bs * 4 + (idx - 2048); const float rsn = rstd1[TP + nr]; const int c0 = 4096 + h * 128 + 8 * li;
;                 k0 = acc1_4(ACC1, nr, c0) * rsn; k1 = acc1_4(ACC1, nr, c0 + 4) * rsn; v0 = acc1_4(ACC1, nr, c0 + 1024) * rsn; v1 = acc1_4(ACC1, nr, c0 + 1028) * rsn; }
;             float dot = (q[0] * k0[0] + q[1] * k0[1]) + (q[2] * k0[2] + q[3] * k0[3]) + (q[4] * k1[0] + q[5] * k1[1]) + (q[6] * k1[2] + q[7] * k1[3]);
;             dot += __shfl_xor(dot, 1); dot += __shfl_xor(dot, 2); dot += __shfl_xor(dot, 4); dot += __shfl_xor(dot, 8);
;             const float s = valid ? dot - sl * (float)(d * j) : -INFINITY;
;             const float mn = fmaxf(m, s), sc = fexp2(m - mn), pe = fexp2(s - mn);
;             l = l * sc + pe;
;             acc[0] = acc[0] * sc + pe * v0[0]; acc[1] = acc[1] * sc + pe * v0[1]; acc[2] = acc[2] * sc + pe * v0[2]; acc[3] = acc[3] * sc + pe * v0[3];
;             acc[4] = acc[4] * sc + pe * v1[0]; acc[5] = acc[5] * sc + pe * v1[1]; acc[6] = acc[6] * sc + pe * v1[2]; acc[7] = acc[7] * sc + pe * v1[3];
;             m = mn;
;         }
.Las_sw4:
	s_waitcnt vmcnt(28)
	v_add_f32_e32 v188, v194, v184
	v_fma_f32 v197, v160, v0, v188
	v_fmac_f32_e32 v197, v161, v1
	v_fmac_f32_e32 v197, v162, v2
	v_fmac_f32_e32 v197, v163, v3
	v_fmac_f32_e32 v197, v164, v4
	v_fmac_f32_e32 v197, v165, v5
	v_fmac_f32_e32 v197, v166, v6
	v_fmac_f32_e32 v197, v167, v7
	s_nop 1
	v_add_f32_dpp v197, v197, v197 row_ror:8 row_mask:0xf bank_mask:0xf
	s_nop 1
	v_add_f32_dpp v197, v197, v197 row_ror:4 row_mask:0xf bank_mask:0xf
	s_nop 1
	v_add_f32_dpp v197, v197, v197 row_ror:2 row_mask:0xf bank_mask:0xf
	s_nop 1
	v_add_f32_dpp v197, v197, v197 row_ror:1 row_mask:0xf bank_mask:0xf
	v_max_f32_e32 v198, v192, v197
	v_sub_f32_e32 v199, v192, v198
	v_sub_f32_e32 v200, v197, v198
	v_exp_f32_e32 v199, v199
	v_exp_f32_e32 v200, v200
	v_mov_b32_e32 v192, v198
	v_fma_f32 v193, v193, v199, v200
	v_mul_f32_e32 v168, v168, v199
	v_mul_f32_e32 v169, v169, v199
	v_mul_f32_e32 v170, v170, v199
	v_mul_f32_e32 v171, v171, v199
	v_mul_f32_e32 v172, v172, v199
	v_mul_f32_e32 v173, v173, v199
	v_mul_f32_e32 v174, v174, v199
	v_mul_f32_e32 v175, v175, v199
	v_fmac_f32_e32 v168, v200, v8
	v_fmac_f32_e32 v169, v200, v9
	v_fmac_f32_e32 v170, v200, v10
	v_fmac_f32_e32 v171, v200, v11
	v_fmac_f32_e32 v172, v200, v12
	v_fmac_f32_e32 v173, v200, v13
	v_fmac_f32_e32 v174, v200, v14
	v_fmac_f32_e32 v175, v200, v15
	v_add_f32_e32 v194, v194, v196
	v_add_u32_e32 v195, s42, v195
	global_load_dwordx4 v[0:3], v195, s[20:21] nt
	global_load_dwordx4 v[4:7], v195, s[20:21] offset:256 nt
	global_load_dwordx4 v[8:11], v195, s[24:25] nt
	global_load_dwordx4 v[12:15], v195, s[24:25] offset:256 nt
	s_waitcnt vmcnt(28)
	v_add_f32_e32 v188, v194, v185
	v_fma_f32 v197, v160, v16, v188
	v_fmac_f32_e32 v197, v161, v17
	v_fmac_f32_e32 v197, v162, v18
	v_fmac_f32_e32 v197, v163, v19
	v_fmac_f32_e32 v197, v164, v20
	v_fmac_f32_e32 v197, v165, v21
	v_fmac_f32_e32 v197, v166, v22
	v_fmac_f32_e32 v197, v167, v23
	s_nop 1
	v_add_f32_dpp v197, v197, v197 row_ror:8 row_mask:0xf bank_mask:0xf
	s_nop 1
	v_add_f32_dpp v197, v197, v197 row_ror:4 row_mask:0xf bank_mask:0xf
	s_nop 1
	v_add_f32_dpp v197, v197, v197 row_ror:2 row_mask:0xf bank_mask:0xf
	s_nop 1
	v_add_f32_dpp v197, v197, v197 row_ror:1 row_mask:0xf bank_mask:0xf
	v_max_f32_e32 v198, v192, v197
	v_sub_f32_e32 v199, v192, v198
	v_sub_f32_e32 v200, v197, v198
	v_exp_f32_e32 v199, v199
	v_exp_f32_e32 v200, v200
	v_mov_b32_e32 v192, v198
	v_fma_f32 v193, v193, v199, v200
	v_mul_f32_e32 v168, v168, v199
	v_mul_f32_e32 v169, v169, v199
	v_mul_f32_e32 v170, v170, v199
	v_mul_f32_e32 v171, v171, v199
	v_mul_f32_e32 v172, v172, v199
	v_mul_f32_e32 v173, v173, v199
	v_mul_f32_e32 v174, v174, v199
	v_mul_f32_e32 v175, v175, v199
	v_fmac_f32_e32 v168, v200, v24
	v_fmac_f32_e32 v169, v200, v25
	v_fmac_f32_e32 v170, v200, v26
	v_fmac_f32_e32 v171, v200, v27
	v_fmac_f32_e32 v172, v200, v28
	v_fmac_f32_e32 v173, v200, v29
	v_fmac_f32_e32 v174, v200, v30
	v_fmac_f32_e32 v175, v200, v31
	v_add_f32_e32 v194, v194, v196
	v_add_u32_e32 v195, s42, v195
	global_load_dwordx4 v[16:19], v195, s[20:21] nt
	global_load_dwordx4 v[20:23], v195, s[20:21] offset:256 nt
	global_load_dwordx4 v[24:27], v195, s[24:25] nt
	global_load_dwordx4 v[28:31], v195, s[24:25] offset:256 nt
	s_waitcnt vmcnt(28)
	v_add_f32_e32 v188, v194, v185
	v_fma_f32 v197, v160, v32, v188
	v_fmac_f32_e32 v197, v161, v33
	v_fmac_f32_e32 v197, v162, v34
	v_fmac_f32_e32 v197, v163, v35
	v_fmac_f32_e32 v197, v164, v36
	v_fmac_f32_e32 v197, v165, v37
	v_fmac_f32_e32 v197, v166, v38
	v_fmac_f32_e32 v197, v167, v39
	s_nop 1
	v_add_f32_dpp v197, v197, v197 row_ror:8 row_mask:0xf bank_mask:0xf
	s_nop 1
	v_add_f32_dpp v197, v197, v197 row_ror:4 row_mask:0xf bank_mask:0xf
	s_nop 1
	v_add_f32_dpp v197, v197, v197 row_ror:2 row_mask:0xf bank_mask:0xf
	s_nop 1
	v_add_f32_dpp v197, v197, v197 row_ror:1 row_mask:0xf bank_mask:0xf
	v_max_f32_e32 v198, v192, v197
	v_sub_f32_e32 v199, v192, v198
	v_sub_f32_e32 v200, v197, v198
	v_exp_f32_e32 v199, v199
	v_exp_f32_e32 v200, v200
	v_mov_b32_e32 v192, v198
	v_fma_f32 v193, v193, v199, v200
	v_mul_f32_e32 v168, v168, v199
	v_mul_f32_e32 v169, v169, v199
	v_mul_f32_e32 v170, v170, v199
	v_mul_f32_e32 v171, v171, v199
	v_mul_f32_e32 v172, v172, v199
	v_mul_f32_e32 v173, v173, v199
	v_mul_f32_e32 v174, v174, v199
	v_mul_f32_e32 v175, v175, v199
	v_fmac_f32_e32 v168, v200, v40
	v_fmac_f32_e32 v169, v200, v41
	v_fmac_f32_e32 v170, v200, v42
	v_fmac_f32_e32 v171, v200, v43
	v_fmac_f32_e32 v172, v200, v44
	v_fmac_f32_e32 v173, v200, v45
	v_fmac_f32_e32 v174, v200, v46
	v_fmac_f32_e32 v175, v200, v47
	v_add_f32_e32 v194, v194, v196
	v_add_u32_e32 v195, s42, v195
	global_load_dwordx4 v[32:35], v195, s[20:21] nt
	global_load_dwordx4 v[36:39], v195, s[20:21] offset:256 nt
	global_load_dwordx4 v[40:43], v195, s[24:25] nt
	global_load_dwordx4 v[44:47], v195, s[24:25] offset:256 nt
	s_waitcnt vmcnt(28)
; __device__ __forceinline__ float fexp2(float x) { return __builtin_amdgcn_exp2f(x); }
; __device__ __forceinline__ void attn_sample_item(const P& p, int wi, int lane) {
;     ...
;         for (int jj = 0; jj < 33; ++jj) {
;             const int j = 4 * jj + kg; const bool valid = j <= 128; const int jc = valid ? j : 128;
;             const int idx = 2048 + i - d * jc;
;             f32x4 k0, k1, v0, v1;
;             if (idx < 2048) { const size_t off = (((size_t)bs * 2048 + idx) * 8 + h) * 128 + 8 * li;
;                 k0 = __builtin_nontemporal_load((const f32x4*)(p.cache_k + off)); k1 = __builtin_nontemporal_load((const f32x4*)(p.cache_k + off + 4)); v0 = __builtin_nontemporal_load((const f32x4*)(p.cache_v + off)); v1 = __builtin_nontemporal_load((const f32x4*)(p.cache_v + off + 4)); }
;             else { const int nr = bs * 4 + (idx - 2048); const float rsn = rstd1[TP + nr]; const int c0 = 4096 + h * 128 + 8 * li;
;                 k0 = acc1_4(ACC1, nr, c0) * rsn; k1 = acc1_4(ACC1, nr, c0 + 4) * rsn; v0 = acc1_4(ACC1, nr, c0 + 1024) * rsn; v1 = acc1_4(ACC1, nr, c0 + 1028) * rsn; }
;             float dot = (q[0] * k0[0] + q[1] * k0[1]) + (q[2] * k0[2] + q[3] * k0[3]) + (q[4] * k1[0] + q[5] * k1[1]) + (q[6] * k1[2] + q[7] * k1[3]);
;             dot += __shfl_xor(dot, 1); dot += __shfl_xor(dot, 2); dot += __shfl_xor(dot, 4); dot += __shfl_xor(dot, 8);
;             const float s = valid ? dot - sl * (float)(d * j) : -INFINITY;
;             const float mn = fmaxf(m, s), sc = fexp2(m - mn), pe = fexp2(s - mn);
;             l = l * sc + pe;
;             acc[0] = acc[0] * sc + pe * v0[0]; acc[1] = acc[1] * sc + pe * v0[1]; acc[2] = acc[2] * sc + pe * v0[2]; acc[3] = acc[3] * sc + pe * v0[3];
;             acc[4] = acc[4] * sc + pe * v1[0]; acc[5] = acc[5] * sc + pe * v1[1]; acc[6] = acc[6] * sc + pe * v1[2]; acc[7] = acc[7] * sc + pe * v1[3];
;             m = mn;
;         }
	v_add_f32_e32 v188, v194, v185
	v_fma_f32 v197, v160, v48, v188
	v_fmac_f32_e32 v197, v161, v49
	v_fmac_f32_e32 v197, v162, v50
	v_fmac_f32_e32 v197, v163, v51
	v_fmac_f32_e32 v197, v164, v52
	v_fmac_f32_e32 v197, v165, v53
	v_fmac_f32_e32 v197, v166, v54
	v_fmac_f32_e32 v197, v167, v55
	s_nop 1
	v_add_f32_dpp v197, v197, v197 row_ror:8 row_mask:0xf bank_mask:0xf
	s_nop 1
	v_add_f32_dpp v197, v197, v197 row_ror:4 row_mask:0xf bank_mask:0xf
	s_nop 1
	v_add_f32_dpp v197, v197, v197 row_ror:2 row_mask:0xf bank_mask:0xf
	s_nop 1
	v_add_f32_dpp v197, v197, v197 row_ror:1 row_mask:0xf bank_mask:0xf
	v_max_f32_e32 v198, v192, v197
	v_sub_f32_e32 v199, v192, v198
	v_sub_f32_e32 v200, v197, v198
	v_exp_f32_e32 v199, v199
	v_exp_f32_e32 v200, v200
	v_mov_b32_e32 v192, v198
	v_fma_f32 v193, v193, v199, v200
	v_mul_f32_e32 v168, v168, v199
	v_mul_f32_e32 v169, v169, v199
	v_mul_f32_e32 v170, v170, v199
	v_mul_f32_e32 v171, v171, v199
	v_mul_f32_e32 v172, v172, v199
	v_mul_f32_e32 v173, v173, v199
	v_mul_f32_e32 v174, v174, v199
	v_mul_f32_e32 v175, v175, v199
	v_fmac_f32_e32 v168, v200, v56
	v_fmac_f32_e32 v169, v200, v57
	v_fmac_f32_e32 v170, v200, v58
	v_fmac_f32_e32 v171, v200, v59
	v_fmac_f32_e32 v172, v200, v60
	v_fmac_f32_e32 v173, v200, v61
	v_fmac_f32_e32 v174, v200, v62
	v_fmac_f32_e32 v175, v200, v63
	v_add_f32_e32 v194, v194, v196
	v_add_u32_e32 v195, s42, v195
	global_load_dwordx4 v[48:51], v195, s[20:21] nt
	global_load_dwordx4 v[52:55], v195, s[20:21] offset:256 nt
	global_load_dwordx4 v[56:59], v195, s[24:25] nt
	global_load_dwordx4 v[60:63], v195, s[24:25] offset:256 nt
	s_waitcnt vmcnt(28)
	v_add_f32_e32 v188, v194, v184
	v_fma_f32 v197, v160, v64, v188
	v_fmac_f32_e32 v197, v161, v65
	v_fmac_f32_e32 v197, v162, v66
	v_fmac_f32_e32 v197, v163, v67
	v_fmac_f32_e32 v197, v164, v68
	v_fmac_f32_e32 v197, v165, v69
	v_fmac_f32_e32 v197, v166, v70
	v_fmac_f32_e32 v197, v167, v71
	s_nop 1
	v_add_f32_dpp v197, v197, v197 row_ror:8 row_mask:0xf bank_mask:0xf
	s_nop 1
	v_add_f32_dpp v197, v197, v197 row_ror:4 row_mask:0xf bank_mask:0xf
	s_nop 1
	v_add_f32_dpp v197, v197, v197 row_ror:2 row_mask:0xf bank_mask:0xf
	s_nop 1
	v_add_f32_dpp v197, v197, v197 row_ror:1 row_mask:0xf bank_mask:0xf
	v_max_f32_e32 v198, v192, v197
	v_sub_f32_e32 v199, v192, v198
	v_sub_f32_e32 v200, v197, v198
	v_exp_f32_e32 v199, v199
	v_exp_f32_e32 v200, v200
	v_mov_b32_e32 v192, v198
	v_fma_f32 v193, v193, v199, v200
	v_mul_f32_e32 v168, v168, v199
	v_mul_f32_e32 v169, v169, v199
	v_mul_f32_e32 v170, v170, v199
	v_mul_f32_e32 v171, v171, v199
	v_mul_f32_e32 v172, v172, v199
	v_mul_f32_e32 v173, v173, v199
	v_mul_f32_e32 v174, v174, v199
	v_mul_f32_e32 v175, v175, v199
	v_fmac_f32_e32 v168, v200, v72
	v_fmac_f32_e32 v169, v200, v73
	v_fmac_f32_e32 v170, v200, v74
	v_fmac_f32_e32 v171, v200, v75
	v_fmac_f32_e32 v172, v200, v76
	v_fmac_f32_e32 v173, v200, v77
	v_fmac_f32_e32 v174, v200, v78
	v_fmac_f32_e32 v175, v200, v79
	v_add_f32_e32 v194, v194, v196
	v_add_u32_e32 v195, s42, v195
	global_load_dwordx4 v[64:67], v195, s[20:21] nt
	global_load_dwordx4 v[68:71], v195, s[20:21] offset:256 nt
	global_load_dwordx4 v[72:75], v195, s[24:25] nt
	global_load_dwordx4 v[76:79], v195, s[24:25] offset:256 nt
	s_waitcnt vmcnt(28)
	v_add_f32_e32 v188, v194, v185
	v_fma_f32 v197, v160, v80, v188
	v_fmac_f32_e32 v197, v161, v81
	v_fmac_f32_e32 v197, v162, v82
	v_fmac_f32_e32 v197, v163, v83
	v_fmac_f32_e32 v197, v164, v84
	v_fmac_f32_e32 v197, v165, v85
	v_fmac_f32_e32 v197, v166, v86
	v_fmac_f32_e32 v197, v167, v87
	s_nop 1
	v_add_f32_dpp v197, v197, v197 row_ror:8 row_mask:0xf bank_mask:0xf
	s_nop 1
	v_add_f32_dpp v197, v197, v197 row_ror:4 row_mask:0xf bank_mask:0xf
	s_nop 1
	v_add_f32_dpp v197, v197, v197 row_ror:2 row_mask:0xf bank_mask:0xf
	s_nop 1
	v_add_f32_dpp v197, v197, v197 row_ror:1 row_mask:0xf bank_mask:0xf
	v_max_f32_e32 v198, v192, v197
	v_sub_f32_e32 v199, v192, v198
	v_sub_f32_e32 v200, v197, v198
	v_exp_f32_e32 v199, v199
	v_exp_f32_e32 v200, v200
	v_mov_b32_e32 v192, v198
	v_fma_f32 v193, v193, v199, v200
	v_mul_f32_e32 v168, v168, v199
	v_mul_f32_e32 v169, v169, v199
	v_mul_f32_e32 v170, v170, v199
	v_mul_f32_e32 v171, v171, v199
	v_mul_f32_e32 v172, v172, v199
	v_mul_f32_e32 v173, v173, v199
	v_mul_f32_e32 v174, v174, v199
	v_mul_f32_e32 v175, v175, v199
	v_fmac_f32_e32 v168, v200, v88
	v_fmac_f32_e32 v169, v200, v89
	v_fmac_f32_e32 v170, v200, v90
	v_fmac_f32_e32 v171, v200, v91
	v_fmac_f32_e32 v172, v200, v92
	v_fmac_f32_e32 v173, v200, v93
	v_fmac_f32_e32 v174, v200, v94
	v_fmac_f32_e32 v175, v200, v95
	v_add_f32_e32 v194, v194, v196
	v_add_u32_e32 v195, s42, v195
	global_load_dwordx4 v[80:83], v195, s[20:21] nt
	global_load_dwordx4 v[84:87], v195, s[20:21] offset:256 nt
	global_load_dwordx4 v[88:91], v195, s[24:25] nt
	global_load_dwordx4 v[92:95], v195, s[24:25] offset:256 nt
	s_waitcnt vmcnt(28)
; __device__ __forceinline__ float fexp2(float x) { return __builtin_amdgcn_exp2f(x); }
; __device__ __forceinline__ void attn_sample_item(const P& p, int wi, int lane) {
;     ...
;         for (int jj = 0; jj < 33; ++jj) {
;             const int j = 4 * jj + kg; const bool valid = j <= 128; const int jc = valid ? j : 128;
;             const int idx = 2048 + i - d * jc;
;             f32x4 k0, k1, v0, v1;
;             if (idx < 2048) { const size_t off = (((size_t)bs * 2048 + idx) * 8 + h) * 128 + 8 * li;
;                 k0 = __builtin_nontemporal_load((const f32x4*)(p.cache_k + off)); k1 = __builtin_nontemporal_load((const f32x4*)(p.cache_k + off + 4)); v0 = __builtin_nontemporal_load((const f32x4*)(p.cache_v + off)); v1 = __builtin_nontemporal_load((const f32x4*)(p.cache_v + off + 4)); }
;             else { const int nr = bs * 4 + (idx - 2048); const float rsn = rstd1[TP + nr]; const int c0 = 4096 + h * 128 + 8 * li;
;                 k0 = acc1_4(ACC1, nr, c0) * rsn; k1 = acc1_4(ACC1, nr, c0 + 4) * rsn; v0 = acc1_4(ACC1, nr, c0 + 1024) * rsn; v1 = acc1_4(ACC1, nr, c0 + 1028) * rsn; }
;             float dot = (q[0] * k0[0] + q[1] * k0[1]) + (q[2] * k0[2] + q[3] * k0[3]) + (q[4] * k1[0] + q[5] * k1[1]) + (q[6] * k1[2] + q[7] * k1[3]);
;             dot += __shfl_xor(dot, 1); dot += __shfl_xor(dot, 2); dot += __shfl_xor(dot, 4); dot += __shfl_xor(dot, 8);
;             const float s = valid ? dot - sl * (float)(d * j) : -INFINITY;
;             const float mn = fmaxf(m, s), sc = fexp2(m - mn), pe = fexp2(s - mn);
;             l = l * sc + pe;
;             acc[0] = acc[0] * sc + pe * v0[0]; acc[1] = acc[1] * sc + pe * v0[1]; acc[2] = acc[2] * sc + pe * v0[2]; acc[3] = acc[3] * sc + pe * v0[3];
;             acc[4] = acc[4] * sc + pe * v1[0]; acc[5] = acc[5] * sc + pe * v1[1]; acc[6] = acc[6] * sc + pe * v1[2]; acc[7] = acc[7] * sc + pe * v1[3];
;             m = mn;
;         }
	v_add_f32_e32 v188, v194, v185
	v_fma_f32 v197, v160, v96, v188
	v_fmac_f32_e32 v197, v161, v97
	v_fmac_f32_e32 v197, v162, v98
	v_fmac_f32_e32 v197, v163, v99
	v_fmac_f32_e32 v197, v164, v100
	v_fmac_f32_e32 v197, v165, v101
	v_fmac_f32_e32 v197, v166, v102
	v_fmac_f32_e32 v197, v167, v103
	s_nop 1
	v_add_f32_dpp v197, v197, v197 row_ror:8 row_mask:0xf bank_mask:0xf
	s_nop 1
	v_add_f32_dpp v197, v197, v197 row_ror:4 row_mask:0xf bank_mask:0xf
	s_nop 1
	v_add_f32_dpp v197, v197, v197 row_ror:2 row_mask:0xf bank_mask:0xf
	s_nop 1
	v_add_f32_dpp v197, v197, v197 row_ror:1 row_mask:0xf bank_mask:0xf
	v_max_f32_e32 v198, v192, v197
	v_sub_f32_e32 v199, v192, v198
	v_sub_f32_e32 v200, v197, v198
	v_exp_f32_e32 v199, v199
	v_exp_f32_e32 v200, v200
	v_mov_b32_e32 v192, v198
	v_fma_f32 v193, v193, v199, v200
	v_mul_f32_e32 v168, v168, v199
	v_mul_f32_e32 v169, v169, v199
	v_mul_f32_e32 v170, v170, v199
	v_mul_f32_e32 v171, v171, v199
	v_mul_f32_e32 v172, v172, v199
	v_mul_f32_e32 v173, v173, v199
	v_mul_f32_e32 v174, v174, v199
	v_mul_f32_e32 v175, v175, v199
	v_fmac_f32_e32 v168, v200, v104
	v_fmac_f32_e32 v169, v200, v105
	v_fmac_f32_e32 v170, v200, v106
	v_fmac_f32_e32 v171, v200, v107
	v_fmac_f32_e32 v172, v200, v108
	v_fmac_f32_e32 v173, v200, v109
	v_fmac_f32_e32 v174, v200, v110
	v_fmac_f32_e32 v175, v200, v111
	v_add_f32_e32 v194, v194, v196
	v_add_u32_e32 v195, s42, v195
	global_load_dwordx4 v[96:99], v195, s[20:21] nt
	global_load_dwordx4 v[100:103], v195, s[20:21] offset:256 nt
	global_load_dwordx4 v[104:107], v195, s[24:25] nt
	global_load_dwordx4 v[108:111], v195, s[24:25] offset:256 nt
	s_waitcnt vmcnt(28)
	v_add_f32_e32 v188, v194, v185
	v_fma_f32 v197, v160, v112, v188
	v_fmac_f32_e32 v197, v161, v113
	v_fmac_f32_e32 v197, v162, v114
	v_fmac_f32_e32 v197, v163, v115
	v_fmac_f32_e32 v197, v164, v116
	v_fmac_f32_e32 v197, v165, v117
	v_fmac_f32_e32 v197, v166, v118
	v_fmac_f32_e32 v197, v167, v119
	s_nop 1
	v_add_f32_dpp v197, v197, v197 row_ror:8 row_mask:0xf bank_mask:0xf
	s_nop 1
	v_add_f32_dpp v197, v197, v197 row_ror:4 row_mask:0xf bank_mask:0xf
	s_nop 1
	v_add_f32_dpp v197, v197, v197 row_ror:2 row_mask:0xf bank_mask:0xf
	s_nop 1
	v_add_f32_dpp v197, v197, v197 row_ror:1 row_mask:0xf bank_mask:0xf
	v_max_f32_e32 v198, v192, v197
	v_sub_f32_e32 v199, v192, v198
	v_sub_f32_e32 v200, v197, v198
	v_exp_f32_e32 v199, v199
	v_exp_f32_e32 v200, v200
	v_mov_b32_e32 v192, v198
	v_fma_f32 v193, v193, v199, v200
	v_mul_f32_e32 v168, v168, v199
	v_mul_f32_e32 v169, v169, v199
	v_mul_f32_e32 v170, v170, v199
	v_mul_f32_e32 v171, v171, v199
	v_mul_f32_e32 v172, v172, v199
	v_mul_f32_e32 v173, v173, v199
	v_mul_f32_e32 v174, v174, v199
	v_mul_f32_e32 v175, v175, v199
	v_fmac_f32_e32 v168, v200, v120
	v_fmac_f32_e32 v169, v200, v121
	v_fmac_f32_e32 v170, v200, v122
	v_fmac_f32_e32 v171, v200, v123
	v_fmac_f32_e32 v172, v200, v124
	v_fmac_f32_e32 v173, v200, v125
	v_fmac_f32_e32 v174, v200, v126
	v_fmac_f32_e32 v175, v200, v127
	v_add_f32_e32 v194, v194, v196
	v_add_u32_e32 v195, s42, v195
	global_load_dwordx4 v[112:115], v195, s[20:21] nt
	global_load_dwordx4 v[116:119], v195, s[20:21] offset:256 nt
	global_load_dwordx4 v[120:123], v195, s[24:25] nt
	global_load_dwordx4 v[124:127], v195, s[24:25] offset:256 nt
	s_add_u32 s33, s33, 1
	s_cmp_lt_u32 s33, 9
	s_cbranch_scc1 .Las_trip
	s_waitcnt vmcnt(28)
	v_add_f32_e32 v188, v194, v184
	v_fma_f32 v197, v160, v0, v188
	v_fmac_f32_e32 v197, v161, v1
	v_fmac_f32_e32 v197, v162, v2
	v_fmac_f32_e32 v197, v163, v3
	v_fmac_f32_e32 v197, v164, v4
	v_fmac_f32_e32 v197, v165, v5
	v_fmac_f32_e32 v197, v166, v6
	v_fmac_f32_e32 v197, v167, v7
	s_nop 1
	v_add_f32_dpp v197, v197, v197 row_ror:8 row_mask:0xf bank_mask:0xf
	s_nop 1
	v_add_f32_dpp v197, v197, v197 row_ror:4 row_mask:0xf bank_mask:0xf
	s_nop 1
	v_add_f32_dpp v197, v197, v197 row_ror:2 row_mask:0xf bank_mask:0xf
	s_nop 1
	v_add_f32_dpp v197, v197, v197 row_ror:1 row_mask:0xf bank_mask:0xf
	v_max_f32_e32 v198, v192, v197
	v_sub_f32_e32 v199, v192, v198
	v_sub_f32_e32 v200, v197, v198
	v_exp_f32_e32 v199, v199
	v_exp_f32_e32 v200, v200
	v_mov_b32_e32 v192, v198
	v_fma_f32 v193, v193, v199, v200
	v_mul_f32_e32 v168, v168, v199
	v_mul_f32_e32 v169, v169, v199
	v_mul_f32_e32 v170, v170, v199
	v_mul_f32_e32 v171, v171, v199
	v_mul_f32_e32 v172, v172, v199
	v_mul_f32_e32 v173, v173, v199
	v_mul_f32_e32 v174, v174, v199
	v_mul_f32_e32 v175, v175, v199
	v_fmac_f32_e32 v168, v200, v8
	v_fmac_f32_e32 v169, v200, v9
	v_fmac_f32_e32 v170, v200, v10
	v_fmac_f32_e32 v171, v200, v11
	v_fmac_f32_e32 v172, v200, v12
	v_fmac_f32_e32 v173, v200, v13
	v_fmac_f32_e32 v174, v200, v14
	v_fmac_f32_e32 v175, v200, v15
	v_add_f32_e32 v194, v194, v196
	s_waitcnt vmcnt(24)
	v_add_f32_e32 v188, v194, v185
	v_fma_f32 v197, v160, v16, v188
	v_fmac_f32_e32 v197, v161, v17
	v_fmac_f32_e32 v197, v162, v18
	v_fmac_f32_e32 v197, v163, v19
	v_fmac_f32_e32 v197, v164, v20
	v_fmac_f32_e32 v197, v165, v21
	v_fmac_f32_e32 v197, v166, v22
	v_fmac_f32_e32 v197, v167, v23
	s_nop 1
	v_add_f32_dpp v197, v197, v197 row_ror:8 row_mask:0xf bank_mask:0xf
	s_nop 1
	v_add_f32_dpp v197, v197, v197 row_ror:4 row_mask:0xf bank_mask:0xf
	s_nop 1
	v_add_f32_dpp v197, v197, v197 row_ror:2 row_mask:0xf bank_mask:0xf
	s_nop 1
	v_add_f32_dpp v197, v197, v197 row_ror:1 row_mask:0xf bank_mask:0xf
	v_max_f32_e32 v198, v192, v197
	v_sub_f32_e32 v199, v192, v198
	v_sub_f32_e32 v200, v197, v198
	v_exp_f32_e32 v199, v199
	v_exp_f32_e32 v200, v200
	v_mov_b32_e32 v192, v198
	v_fma_f32 v193, v193, v199, v200
	v_mul_f32_e32 v168, v168, v199
	v_mul_f32_e32 v169, v169, v199
	v_mul_f32_e32 v170, v170, v199
	v_mul_f32_e32 v171, v171, v199
	v_mul_f32_e32 v172, v172, v199
	v_mul_f32_e32 v173, v173, v199
	v_mul_f32_e32 v174, v174, v199
	v_mul_f32_e32 v175, v175, v199
	v_fmac_f32_e32 v168, v200, v24
	v_fmac_f32_e32 v169, v200, v25
	v_fmac_f32_e32 v170, v200, v26
	v_fmac_f32_e32 v171, v200, v27
	v_fmac_f32_e32 v172, v200, v28
	v_fmac_f32_e32 v173, v200, v29
	v_fmac_f32_e32 v174, v200, v30
	v_fmac_f32_e32 v175, v200, v31
	v_add_f32_e32 v194, v194, v196
	s_waitcnt vmcnt(20)
; __device__ __forceinline__ float fexp2(float x) { return __builtin_amdgcn_exp2f(x); }
; __device__ __forceinline__ void attn_sample_item(const P& p, int wi, int lane) {
;     ...
;         for (int jj = 0; jj < 33; ++jj) {
;             const int j = 4 * jj + kg; const bool valid = j <= 128; const int jc = valid ? j : 128;
;             const int idx = 2048 + i - d * jc;
;             f32x4 k0, k1, v0, v1;
;             if (idx < 2048) { const size_t off = (((size_t)bs * 2048 + idx) * 8 + h) * 128 + 8 * li;
;                 k0 = __builtin_nontemporal_load((const f32x4*)(p.cache_k + off)); k1 = __builtin_nontemporal_load((const f32x4*)(p.cache_k + off + 4)); v0 = __builtin_nontemporal_load((const f32x4*)(p.cache_v + off)); v1 = __builtin_nontemporal_load((const f32x4*)(p.cache_v + off + 4)); }
;             else { const int nr = bs * 4 + (idx - 2048); const float rsn = rstd1[TP + nr]; const int c0 = 4096 + h * 128 + 8 * li;
;                 k0 = acc1_4(ACC1, nr, c0) * rsn; k1 = acc1_4(ACC1, nr, c0 + 4) * rsn; v0 = acc1_4(ACC1, nr, c0 + 1024) * rsn; v1 = acc1_4(ACC1, nr, c0 + 1028) * rsn; }
;             float dot = (q[0] * k0[0] + q[1] * k0[1]) + (q[2] * k0[2] + q[3] * k0[3]) + (q[4] * k1[0] + q[5] * k1[1]) + (q[6] * k1[2] + q[7] * k1[3]);
;             dot += __shfl_xor(dot, 1); dot += __shfl_xor(dot, 2); dot += __shfl_xor(dot, 4); dot += __shfl_xor(dot, 8);
;             const float s = valid ? dot - sl * (float)(d * j) : -INFINITY;
;             const float mn = fmaxf(m, s), sc = fexp2(m - mn), pe = fexp2(s - mn);
;             l = l * sc + pe;
;             acc[0] = acc[0] * sc + pe * v0[0]; acc[1] = acc[1] * sc + pe * v0[1]; acc[2] = acc[2] * sc + pe * v0[2]; acc[3] = acc[3] * sc + pe * v0[3];
;             acc[4] = acc[4] * sc + pe * v1[0]; acc[5] = acc[5] * sc + pe * v1[1]; acc[6] = acc[6] * sc + pe * v1[2]; acc[7] = acc[7] * sc + pe * v1[3];
;             m = mn;
;         }
	v_add_f32_e32 v188, v194, v185
	v_fma_f32 v197, v160, v32, v188
	v_fmac_f32_e32 v197, v161, v33
	v_fmac_f32_e32 v197, v162, v34
	v_fmac_f32_e32 v197, v163, v35
	v_fmac_f32_e32 v197, v164, v36
	v_fmac_f32_e32 v197, v165, v37
	v_fmac_f32_e32 v197, v166, v38
	v_fmac_f32_e32 v197, v167, v39
	s_nop 1
	v_add_f32_dpp v197, v197, v197 row_ror:8 row_mask:0xf bank_mask:0xf
	s_nop 1
	v_add_f32_dpp v197, v197, v197 row_ror:4 row_mask:0xf bank_mask:0xf
	s_nop 1
	v_add_f32_dpp v197, v197, v197 row_ror:2 row_mask:0xf bank_mask:0xf
	s_nop 1
	v_add_f32_dpp v197, v197, v197 row_ror:1 row_mask:0xf bank_mask:0xf
	v_max_f32_e32 v198, v192, v197
	v_sub_f32_e32 v199, v192, v198
	v_sub_f32_e32 v200, v197, v198
	v_exp_f32_e32 v199, v199
	v_exp_f32_e32 v200, v200
	v_mov_b32_e32 v192, v198
	v_fma_f32 v193, v193, v199, v200
	v_mul_f32_e32 v168, v168, v199
	v_mul_f32_e32 v169, v169, v199
	v_mul_f32_e32 v170, v170, v199
	v_mul_f32_e32 v171, v171, v199
	v_mul_f32_e32 v172, v172, v199
	v_mul_f32_e32 v173, v173, v199
	v_mul_f32_e32 v174, v174, v199
	v_mul_f32_e32 v175, v175, v199
	v_fmac_f32_e32 v168, v200, v40
	v_fmac_f32_e32 v169, v200, v41
	v_fmac_f32_e32 v170, v200, v42
	v_fmac_f32_e32 v171, v200, v43
	v_fmac_f32_e32 v172, v200, v44
	v_fmac_f32_e32 v173, v200, v45
	v_fmac_f32_e32 v174, v200, v46
	v_fmac_f32_e32 v175, v200, v47
	v_add_f32_e32 v194, v194, v196
	s_waitcnt vmcnt(16)
	v_add_f32_e32 v188, v194, v185
	v_fma_f32 v197, v160, v48, v188
	v_fmac_f32_e32 v197, v161, v49
	v_fmac_f32_e32 v197, v162, v50
	v_fmac_f32_e32 v197, v163, v51
	v_fmac_f32_e32 v197, v164, v52
	v_fmac_f32_e32 v197, v165, v53
	v_fmac_f32_e32 v197, v166, v54
	v_fmac_f32_e32 v197, v167, v55
	s_nop 1
	v_add_f32_dpp v197, v197, v197 row_ror:8 row_mask:0xf bank_mask:0xf
	s_nop 1
	v_add_f32_dpp v197, v197, v197 row_ror:4 row_mask:0xf bank_mask:0xf
	s_nop 1
	v_add_f32_dpp v197, v197, v197 row_ror:2 row_mask:0xf bank_mask:0xf
	s_nop 1
	v_add_f32_dpp v197, v197, v197 row_ror:1 row_mask:0xf bank_mask:0xf
	v_max_f32_e32 v198, v192, v197
	v_sub_f32_e32 v199, v192, v198
	v_sub_f32_e32 v200, v197, v198
	v_exp_f32_e32 v199, v199
	v_exp_f32_e32 v200, v200
	v_mov_b32_e32 v192, v198
	v_fma_f32 v193, v193, v199, v200
	v_mul_f32_e32 v168, v168, v199
	v_mul_f32_e32 v169, v169, v199
	v_mul_f32_e32 v170, v170, v199
	v_mul_f32_e32 v171, v171, v199
	v_mul_f32_e32 v172, v172, v199
	v_mul_f32_e32 v173, v173, v199
	v_mul_f32_e32 v174, v174, v199
	v_mul_f32_e32 v175, v175, v199
	v_fmac_f32_e32 v168, v200, v56
	v_fmac_f32_e32 v169, v200, v57
	v_fmac_f32_e32 v170, v200, v58
	v_fmac_f32_e32 v171, v200, v59
	v_fmac_f32_e32 v172, v200, v60
	v_fmac_f32_e32 v173, v200, v61
	v_fmac_f32_e32 v174, v200, v62
	v_fmac_f32_e32 v175, v200, v63
	v_add_f32_e32 v194, v194, v196
	s_waitcnt vmcnt(12)
	v_add_f32_e32 v188, v194, v184
	v_fma_f32 v197, v160, v64, v188
	v_fmac_f32_e32 v197, v161, v65
	v_fmac_f32_e32 v197, v162, v66
	v_fmac_f32_e32 v197, v163, v67
	v_fmac_f32_e32 v197, v164, v68
	v_fmac_f32_e32 v197, v165, v69
	v_fmac_f32_e32 v197, v166, v70
	v_fmac_f32_e32 v197, v167, v71
	s_nop 1
	v_add_f32_dpp v197, v197, v197 row_ror:8 row_mask:0xf bank_mask:0xf
	s_nop 1
	v_add_f32_dpp v197, v197, v197 row_ror:4 row_mask:0xf bank_mask:0xf
	s_nop 1
	v_add_f32_dpp v197, v197, v197 row_ror:2 row_mask:0xf bank_mask:0xf
	s_nop 1
	v_add_f32_dpp v197, v197, v197 row_ror:1 row_mask:0xf bank_mask:0xf
	v_max_f32_e32 v198, v192, v197
	v_sub_f32_e32 v199, v192, v198
	v_sub_f32_e32 v200, v197, v198
	v_exp_f32_e32 v199, v199
	v_exp_f32_e32 v200, v200
	v_mov_b32_e32 v192, v198
	v_fma_f32 v193, v193, v199, v200
	v_mul_f32_e32 v168, v168, v199
	v_mul_f32_e32 v169, v169, v199
	v_mul_f32_e32 v170, v170, v199
	v_mul_f32_e32 v171, v171, v199
	v_mul_f32_e32 v172, v172, v199
	v_mul_f32_e32 v173, v173, v199
	v_mul_f32_e32 v174, v174, v199
	v_mul_f32_e32 v175, v175, v199
	v_fmac_f32_e32 v168, v200, v72
	v_fmac_f32_e32 v169, v200, v73
	v_fmac_f32_e32 v170, v200, v74
	v_fmac_f32_e32 v171, v200, v75
	v_fmac_f32_e32 v172, v200, v76
	v_fmac_f32_e32 v173, v200, v77
	v_fmac_f32_e32 v174, v200, v78
	v_fmac_f32_e32 v175, v200, v79
	v_add_f32_e32 v194, v194, v196
	s_waitcnt vmcnt(8)
	v_add_f32_e32 v188, v194, v185
	v_fma_f32 v197, v160, v80, v188
	v_fmac_f32_e32 v197, v161, v81
	v_fmac_f32_e32 v197, v162, v82
	v_fmac_f32_e32 v197, v163, v83
	v_fmac_f32_e32 v197, v164, v84
	v_fmac_f32_e32 v197, v165, v85
	v_fmac_f32_e32 v197, v166, v86
	v_fmac_f32_e32 v197, v167, v87
	s_nop 1
	v_add_f32_dpp v197, v197, v197 row_ror:8 row_mask:0xf bank_mask:0xf
	s_nop 1
	v_add_f32_dpp v197, v197, v197 row_ror:4 row_mask:0xf bank_mask:0xf
	s_nop 1
	v_add_f32_dpp v197, v197, v197 row_ror:2 row_mask:0xf bank_mask:0xf
	s_nop 1
	v_add_f32_dpp v197, v197, v197 row_ror:1 row_mask:0xf bank_mask:0xf
	v_max_f32_e32 v198, v192, v197
	v_sub_f32_e32 v199, v192, v198
	v_sub_f32_e32 v200, v197, v198
	v_exp_f32_e32 v199, v199
	v_exp_f32_e32 v200, v200
	v_mov_b32_e32 v192, v198
	v_fma_f32 v193, v193, v199, v200
	v_mul_f32_e32 v168, v168, v199
	v_mul_f32_e32 v169, v169, v199
	v_mul_f32_e32 v170, v170, v199
	v_mul_f32_e32 v171, v171, v199
	v_mul_f32_e32 v172, v172, v199
	v_mul_f32_e32 v173, v173, v199
	v_mul_f32_e32 v174, v174, v199
	v_mul_f32_e32 v175, v175, v199
	v_fmac_f32_e32 v168, v200, v88
	v_fmac_f32_e32 v169, v200, v89
	v_fmac_f32_e32 v170, v200, v90
	v_fmac_f32_e32 v171, v200, v91
	v_fmac_f32_e32 v172, v200, v92
	v_fmac_f32_e32 v173, v200, v93
	v_fmac_f32_e32 v174, v200, v94
	v_fmac_f32_e32 v175, v200, v95
	v_add_f32_e32 v194, v194, v196
	s_waitcnt vmcnt(4)
; __device__ __forceinline__ float fexp2(float x) { return __builtin_amdgcn_exp2f(x); }
; __device__ __forceinline__ void attn_sample_item(const P& p, int wi, int lane) {
;     ...
;         for (int jj = 0; jj < 33; ++jj) {
;             const int j = 4 * jj + kg; const bool valid = j <= 128; const int jc = valid ? j : 128;
;             const int idx = 2048 + i - d * jc;
;             f32x4 k0, k1, v0, v1;
;             if (idx < 2048) { const size_t off = (((size_t)bs * 2048 + idx) * 8 + h) * 128 + 8 * li;
;                 k0 = __builtin_nontemporal_load((const f32x4*)(p.cache_k + off)); k1 = __builtin_nontemporal_load((const f32x4*)(p.cache_k + off + 4)); v0 = __builtin_nontemporal_load((const f32x4*)(p.cache_v + off)); v1 = __builtin_nontemporal_load((const f32x4*)(p.cache_v + off + 4)); }
;             else { const int nr = bs * 4 + (idx - 2048); const float rsn = rstd1[TP + nr]; const int c0 = 4096 + h * 128 + 8 * li;
;                 k0 = acc1_4(ACC1, nr, c0) * rsn; k1 = acc1_4(ACC1, nr, c0 + 4) * rsn; v0 = acc1_4(ACC1, nr, c0 + 1024) * rsn; v1 = acc1_4(ACC1, nr, c0 + 1028) * rsn; }
;             float dot = (q[0] * k0[0] + q[1] * k0[1]) + (q[2] * k0[2] + q[3] * k0[3]) + (q[4] * k1[0] + q[5] * k1[1]) + (q[6] * k1[2] + q[7] * k1[3]);
;             dot += __shfl_xor(dot, 1); dot += __shfl_xor(dot, 2); dot += __shfl_xor(dot, 4); dot += __shfl_xor(dot, 8);
;             const float s = valid ? dot - sl * (float)(d * j) : -INFINITY;
;             const float mn = fmaxf(m, s), sc = fexp2(m - mn), pe = fexp2(s - mn);
;             l = l * sc + pe;
;             acc[0] = acc[0] * sc + pe * v0[0]; acc[1] = acc[1] * sc + pe * v0[1]; acc[2] = acc[2] * sc + pe * v0[2]; acc[3] = acc[3] * sc + pe * v0[3];
;             acc[4] = acc[4] * sc + pe * v1[0]; acc[5] = acc[5] * sc + pe * v1[1]; acc[6] = acc[6] * sc + pe * v1[2]; acc[7] = acc[7] * sc + pe * v1[3];
;             m = mn;
;         }
;     }
;     float mt = fmaxf(m, __shfl_xor(m, 16)); mt = fmaxf(mt, __shfl_xor(mt, 32));
;     const float f = fexp2(m - mt);
;     l *= f; l += __shfl_xor(l, 16); l += __shfl_xor(l, 32);
;     const float inv = 1.f / l;
;     float* o = (float*)(ws + O_ATTS) + (size_t)srow * 1024 + h * 128 + 8 * li;
; #pragma unroll
;     for (int e = 0; e < 8; ++e) { float a = acc[e] * f; a += __shfl_xor(a, 16); a += __shfl_xor(a, 32); acc[e] = a * inv; }
	v_add_f32_e32 v188, v194, v185
	v_fma_f32 v197, v160, v96, v188
	v_fmac_f32_e32 v197, v161, v97
	v_fmac_f32_e32 v197, v162, v98
	v_fmac_f32_e32 v197, v163, v99
	v_fmac_f32_e32 v197, v164, v100
	v_fmac_f32_e32 v197, v165, v101
	v_fmac_f32_e32 v197, v166, v102
	v_fmac_f32_e32 v197, v167, v103
	s_nop 1
	v_add_f32_dpp v197, v197, v197 row_ror:8 row_mask:0xf bank_mask:0xf
	s_nop 1
	v_add_f32_dpp v197, v197, v197 row_ror:4 row_mask:0xf bank_mask:0xf
	s_nop 1
	v_add_f32_dpp v197, v197, v197 row_ror:2 row_mask:0xf bank_mask:0xf
	s_nop 1
	v_add_f32_dpp v197, v197, v197 row_ror:1 row_mask:0xf bank_mask:0xf
	v_max_f32_e32 v198, v192, v197
	v_sub_f32_e32 v199, v192, v198
	v_sub_f32_e32 v200, v197, v198
	v_exp_f32_e32 v199, v199
	v_exp_f32_e32 v200, v200
	v_mov_b32_e32 v192, v198
	v_fma_f32 v193, v193, v199, v200
	v_mul_f32_e32 v168, v168, v199
	v_mul_f32_e32 v169, v169, v199
	v_mul_f32_e32 v170, v170, v199
	v_mul_f32_e32 v171, v171, v199
	v_mul_f32_e32 v172, v172, v199
	v_mul_f32_e32 v173, v173, v199
	v_mul_f32_e32 v174, v174, v199
	v_mul_f32_e32 v175, v175, v199
	v_fmac_f32_e32 v168, v200, v104
	v_fmac_f32_e32 v169, v200, v105
	v_fmac_f32_e32 v170, v200, v106
	v_fmac_f32_e32 v171, v200, v107
	v_fmac_f32_e32 v172, v200, v108
	v_fmac_f32_e32 v173, v200, v109
	v_fmac_f32_e32 v174, v200, v110
	v_fmac_f32_e32 v175, v200, v111
	v_add_f32_e32 v194, v194, v196
	s_waitcnt vmcnt(0)
	v_add_f32_e32 v188, v194, v185
	v_fma_f32 v197, v160, v112, v188
	v_fmac_f32_e32 v197, v161, v113
	v_fmac_f32_e32 v197, v162, v114
	v_fmac_f32_e32 v197, v163, v115
	v_fmac_f32_e32 v197, v164, v116
	v_fmac_f32_e32 v197, v165, v117
	v_fmac_f32_e32 v197, v166, v118
	v_fmac_f32_e32 v197, v167, v119
	s_nop 1
	v_add_f32_dpp v197, v197, v197 row_ror:8 row_mask:0xf bank_mask:0xf
	s_nop 1
	v_add_f32_dpp v197, v197, v197 row_ror:4 row_mask:0xf bank_mask:0xf
	s_nop 1
	v_add_f32_dpp v197, v197, v197 row_ror:2 row_mask:0xf bank_mask:0xf
	s_nop 1
	v_add_f32_dpp v197, v197, v197 row_ror:1 row_mask:0xf bank_mask:0xf
	v_max_f32_e32 v198, v192, v197
	v_sub_f32_e32 v199, v192, v198
	v_sub_f32_e32 v200, v197, v198
	v_exp_f32_e32 v199, v199
	v_exp_f32_e32 v200, v200
	v_mov_b32_e32 v192, v198
	v_fma_f32 v193, v193, v199, v200
	v_mul_f32_e32 v168, v168, v199
	v_mul_f32_e32 v169, v169, v199
	v_mul_f32_e32 v170, v170, v199
	v_mul_f32_e32 v171, v171, v199
	v_mul_f32_e32 v172, v172, v199
	v_mul_f32_e32 v173, v173, v199
	v_mul_f32_e32 v174, v174, v199
	v_mul_f32_e32 v175, v175, v199
	v_fmac_f32_e32 v168, v200, v120
	v_fmac_f32_e32 v169, v200, v121
	v_fmac_f32_e32 v170, v200, v122
	v_fmac_f32_e32 v171, v200, v123
	v_fmac_f32_e32 v172, v200, v124
	v_fmac_f32_e32 v173, v200, v125
	v_fmac_f32_e32 v174, v200, v126
	v_fmac_f32_e32 v175, v200, v127
	v_and_b32_e32 v182, 63, v230
	v_xor_b32_e32 v183, 16, v182
	v_lshlrev_b32_e32 v183, 2, v183
	v_xor_b32_e32 v182, 32, v182
	v_lshlrev_b32_e32 v182, 2, v182
	ds_bpermute_b32 v197, v183, v192
	s_waitcnt lgkmcnt(0)
	v_max_f32_e32 v198, v192, v197
	ds_bpermute_b32 v197, v182, v198
	s_waitcnt lgkmcnt(0)
	v_max_f32_e32 v198, v198, v197
	v_sub_f32_e32 v199, v192, v198
	v_exp_f32_e32 v199, v199
	s_nop 0
	v_mul_f32_e32 v193, v193, v199
	v_mul_f32_e32 v168, v168, v199
	v_mul_f32_e32 v169, v169, v199
	v_mul_f32_e32 v170, v170, v199
	v_mul_f32_e32 v171, v171, v199
	v_mul_f32_e32 v172, v172, v199
	v_mul_f32_e32 v173, v173, v199
	v_mul_f32_e32 v174, v174, v199
	v_mul_f32_e32 v175, v175, v199
	ds_bpermute_b32 v0, v183, v193
	ds_bpermute_b32 v1, v183, v168
	ds_bpermute_b32 v2, v183, v169
	ds_bpermute_b32 v3, v183, v170
	ds_bpermute_b32 v4, v183, v171
	ds_bpermute_b32 v5, v183, v172
	ds_bpermute_b32 v6, v183, v173
	ds_bpermute_b32 v7, v183, v174
	ds_bpermute_b32 v8, v183, v175
	s_waitcnt lgkmcnt(0)
	v_add_f32_e32 v193, v193, v0
	v_add_f32_e32 v168, v168, v1
	v_add_f32_e32 v169, v169, v2
	v_add_f32_e32 v170, v170, v3
	v_add_f32_e32 v171, v171, v4
	v_add_f32_e32 v172, v172, v5
	v_add_f32_e32 v173, v173, v6
	v_add_f32_e32 v174, v174, v7
	v_add_f32_e32 v175, v175, v8
	ds_bpermute_b32 v0, v182, v193
	ds_bpermute_b32 v1, v182, v168
	ds_bpermute_b32 v2, v182, v169
	ds_bpermute_b32 v3, v182, v170
	ds_bpermute_b32 v4, v182, v171
	ds_bpermute_b32 v5, v182, v172
	ds_bpermute_b32 v6, v182, v173
	ds_bpermute_b32 v7, v182, v174
	ds_bpermute_b32 v8, v182, v175
	s_waitcnt lgkmcnt(0)
	v_add_f32_e32 v193, v193, v0
	v_add_f32_e32 v168, v168, v1
	v_add_f32_e32 v169, v169, v2
	v_add_f32_e32 v170, v170, v3
	v_add_f32_e32 v171, v171, v4
	v_add_f32_e32 v172, v172, v5
	v_add_f32_e32 v173, v173, v6
	v_add_f32_e32 v174, v174, v7
	v_add_f32_e32 v175, v175, v8
	v_rcp_f32_e32 v197, v193
	s_nop 0
	v_fma_f32 v198, -v193, v197, 1.0
	v_fma_f32 v197, v198, v197, v197
	v_mul_f32_e32 v168, v168, v197
	v_mul_f32_e32 v169, v169, v197
	v_mul_f32_e32 v170, v170, v197
	v_mul_f32_e32 v171, v171, v197
	v_mul_f32_e32 v172, v172, v197
	v_mul_f32_e32 v173, v173, v197
	v_mul_f32_e32 v174, v174, v197
	v_mul_f32_e32 v175, v175, v197
	v_and_b32_e32 v182, 15, v230
	v_lshlrev_b32_e32 v182, 4, v182
	s_lshl_b32 s43, s17, 12
	s_add_u32 s43, s43, s23
	v_add_u32_e32 v182, s43, v182
	s_mov_b64 exec, 0xffff
	global_store_dwordx4 v182, v[168:171], s[30:31]
	global_store_dwordx4 v182, v[172:175], s[30:31] offset:256
	s_mov_b64 exec, -1
	s_add_i32 s3, s3, s77
	s_cmpk_gt_i32 s3, 0x3ff
	s_cbranch_scc0 .Las_item
